# EpiProj: 8 rstd loads hoisted + counted vmcnt; EpiUp sub-pass 1: one hoisted vmcnt(0) replaces 4 per-branch vmcnt(0) that drained stores
# speedup vs baseline: 1.0320x; 1.0045x over previous
; #define PG8_STAGE(bufoff, gbase, voff) do { _Pragma("unroll") for (int _i = 0; _i < 2; ++_i) \
;         __builtin_amdgcn_global_load_lds((const unsigned*)((const char*)(gbase) + (voff)[_i]), (LAS unsigned*)(lds + (bufoff) + ldsw + _i * 8192), 16, 0, 0); } while (0)
; #define PG8_LDA(dst, b, h) do { _Pragma("unroll") for (int m = 0; m < 4; ++m) _Pragma("unroll") for (int k = 0; k < 2; ++k) dst[m][k] = *(const LAS bf16x8*)(lds + PG8_SA(b, h) + aoff + m * 2048 + k * 1024); } while (0)
; #define PG8_LDB(dst, b, h) do { _Pragma("unroll") for (int n = 0; n < 2; ++n) _Pragma("unroll") for (int k = 0; k < 2; ++k) dst[n][k] = *(const LAS bf16x8*)(lds + PG8_SB(b, h) + boff + n * 2048 + k * 1024); } while (0)
; #define PG8_MMA(ai, bj, At, Bt) do { __builtin_amdgcn_s_setprio(1); _Pragma("unroll") for (int m = 0; m < 4; ++m) _Pragma("unroll") for (int n = 0; n < 2; ++n) _Pragma("unroll") for (int k = 0; k < 2; ++k) \
;         acc[ai][bj][m][n] = __builtin_amdgcn_mfma_f32_16x16x32_bf16(Bt[n][k], At[m][k], acc[ai][bj][m][n], 0, 0, 0); __builtin_amdgcn_s_setprio(0); } while (0)
; #define PG8_WAIT_L(n) asm volatile("s_waitcnt lgkmcnt(" #n ")" ::: "memory")
; #define PG8_BAR __builtin_amdgcn_s_barrier()
; #define PG8_SCHED __builtin_amdgcn_sched_barrier(0)
; template <class Epi>
; __device__ __forceinline__ void gemm_phase(LAS unsigned char* lds, const Gemm g, const StaticOrder& S, const Epi& E) {
;     ...
;             PG8_LDB(B0, 0, 0); PG8_SCHED; PG8_LDA(At, 0, 0); PG8_STAGE(PG8_SA(1, 1), a1 + hstepA, voffA);
;             PG8_WAIT_L(8); PG8_BAR; PG8_WAIT_L(0); PG8_MMA(0, 0, At, B0); PG8_BAR; PG8_SCHED;
;             PG8_LDB(B1, 0, 1); PG8_STAGE(PG8_SB(0, 0), b2, voffB);
;             PG8_BAR; PG8_WAIT_L(0); PG8_MMA(0, 1, At, B1); PG8_BAR;
;             PG8_LDA(At, 0, 1); PG8_STAGE(PG8_SA(0, 0), a2, voffA);
;             PG8_BAR; PG8_WAIT_L(0); PG8_MMA(1, 0, At, B0); PG8_BAR; PG8_SCHED;
;             PG8_STAGE(PG8_SB(0, 1), b2 + hstepB, voffB);
.LBB0_162:
	ds_read_b128 v[144:147], v158
	ds_read_b128 v[148:151], v158 offset:1024
	ds_read_b128 v[162:165], v158 offset:2048
	ds_read_b128 v[166:169], v158 offset:3072
	s_add_u32 s34, s30, 0xfffc0080
	s_addc_u32 s35, s31, -1
	s_cmp_eq_u32 s52, 12
	s_cselect_b32 s37, s15, s35
	s_cselect_b32 s36, s48, s34
	s_cselect_b32 s35, s13, s51
	s_cselect_b32 s34, s49, s50
	v_lshl_add_u64 v[174:175], s[30:31], 0, v[136:137]
	s_add_i32 m0, s25, 0xc000
	ds_read_b128 v[170:173], v159
	ds_read_b128 v[178:181], v159 offset:1024
	ds_read_b128 v[182:185], v159 offset:2048
	ds_read_b128 v[186:189], v159 offset:3072
	ds_read_b128 v[190:193], v159 offset:4096
	ds_read_b128 v[194:197], v159 offset:5120
	ds_read_b128 v[198:201], v159 offset:6144
	ds_read_b128 v[202:205], v159 offset:7168
	global_load_lds_dwordx4 v[174:175], off
	v_lshl_add_u64 v[174:175], s[30:31], 0, v[138:139]
	s_add_i32 m0, s25, 0xe000
	s_nop 0
	global_load_lds_dwordx4 v[174:175], off
	s_waitcnt lgkmcnt(8)
	s_barrier
	s_waitcnt lgkmcnt(0)
	s_setprio 1
	s_waitcnt lgkmcnt(0)
	v_mfma_f32_16x16x32_bf16 v[124:127], v[144:147], v[170:173], v[124:127]
	v_mfma_f32_16x16x32_bf16 v[120:123], v[162:165], v[170:173], v[120:123]
	v_mfma_f32_16x16x32_bf16 v[108:111], v[144:147], v[182:185], v[108:111]
	v_mfma_f32_16x16x32_bf16 v[104:107], v[162:165], v[182:185], v[104:107]
	v_mfma_f32_16x16x32_bf16 v[92:95], v[144:147], v[190:193], v[92:95]
	v_mfma_f32_16x16x32_bf16 v[88:91], v[162:165], v[190:193], v[88:91]
	v_mfma_f32_16x16x32_bf16 v[76:79], v[144:147], v[198:201], v[76:79]
	v_mfma_f32_16x16x32_bf16 v[72:75], v[162:165], v[198:201], v[72:75]
	v_mfma_f32_16x16x32_bf16 v[124:127], v[148:151], v[178:181], v[124:127]
	v_mfma_f32_16x16x32_bf16 v[120:123], v[166:169], v[178:181], v[120:123]
	v_mfma_f32_16x16x32_bf16 v[108:111], v[148:151], v[186:189], v[108:111]
	v_mfma_f32_16x16x32_bf16 v[104:107], v[166:169], v[186:189], v[104:107]
	v_mfma_f32_16x16x32_bf16 v[92:95], v[148:151], v[194:197], v[92:95]
	v_mfma_f32_16x16x32_bf16 v[88:91], v[166:169], v[194:197], v[88:91]
	v_mfma_f32_16x16x32_bf16 v[76:79], v[148:151], v[202:205], v[76:79]
	v_mfma_f32_16x16x32_bf16 v[72:75], v[166:169], v[202:205], v[72:75]
	s_setprio 0
	s_barrier
	s_add_i32 s53, s45, s29
	v_lshl_add_u64 v[174:175], s[34:35], 0, v[130:131]
	s_mov_b32 m0, s53
	ds_read_b128 v[206:209], v160
	ds_read_b128 v[210:213], v160 offset:1024
	ds_read_b128 v[214:217], v160 offset:2048
	ds_read_b128 v[218:221], v160 offset:3072
	global_load_lds_dwordx4 v[174:175], off
	v_lshl_add_u64 v[222:223], s[34:35], 0, v[134:135]
	s_add_i32 m0, s53, 0x2000
	s_nop 0
	global_load_lds_dwordx4 v[222:223], off
	s_barrier
	s_waitcnt lgkmcnt(0)
	s_setprio 1
	s_waitcnt lgkmcnt(0)
	v_mfma_f32_16x16x32_bf16 v[116:119], v[206:209], v[170:173], v[116:119]
	v_mfma_f32_16x16x32_bf16 v[112:115], v[214:217], v[170:173], v[112:115]
	v_mfma_f32_16x16x32_bf16 v[100:103], v[206:209], v[182:185], v[100:103]
	v_mfma_f32_16x16x32_bf16 v[96:99], v[214:217], v[182:185], v[96:99]
	v_mfma_f32_16x16x32_bf16 v[84:87], v[206:209], v[190:193], v[84:87]
	v_mfma_f32_16x16x32_bf16 v[80:83], v[214:217], v[190:193], v[80:83]
	v_mfma_f32_16x16x32_bf16 v[68:71], v[206:209], v[198:201], v[68:71]
	v_mfma_f32_16x16x32_bf16 v[64:67], v[214:217], v[198:201], v[64:67]
	v_mfma_f32_16x16x32_bf16 v[116:119], v[210:213], v[178:181], v[116:119]
	v_mfma_f32_16x16x32_bf16 v[112:115], v[218:221], v[178:181], v[112:115]
	v_mfma_f32_16x16x32_bf16 v[100:103], v[210:213], v[186:189], v[100:103]
	v_mfma_f32_16x16x32_bf16 v[96:99], v[218:221], v[186:189], v[96:99]
	v_mfma_f32_16x16x32_bf16 v[84:87], v[210:213], v[194:197], v[84:87]
	v_mfma_f32_16x16x32_bf16 v[80:83], v[218:221], v[194:197], v[80:83]
	v_mfma_f32_16x16x32_bf16 v[68:71], v[210:213], v[202:205], v[68:71]
	v_mfma_f32_16x16x32_bf16 v[64:67], v[218:221], v[202:205], v[64:67]
	s_setprio 0
	s_mov_b32 m0, s25
	v_lshl_add_u64 v[224:225], s[36:37], 0, v[128:129]
	s_barrier
	ds_read_b128 v[170:173], v159 offset:16384
	ds_read_b128 v[178:181], v159 offset:17408
	ds_read_b128 v[182:185], v159 offset:18432
	ds_read_b128 v[186:189], v159 offset:19456
	ds_read_b128 v[190:193], v159 offset:20480
	ds_read_b128 v[194:197], v159 offset:21504
	ds_read_b128 v[198:201], v159 offset:22528
	ds_read_b128 v[202:205], v159 offset:23552
	global_load_lds_dwordx4 v[224:225], off
	v_lshl_add_u64 v[226:227], s[36:37], 0, v[132:133]
	s_mov_b32 m0, s33
	s_nop 0
	global_load_lds_dwordx4 v[226:227], off
	s_barrier
	s_waitcnt lgkmcnt(0)
	s_setprio 1
	s_waitcnt lgkmcnt(0)
	v_mfma_f32_16x16x32_bf16 v[60:63], v[144:147], v[170:173], v[60:63]
	v_mfma_f32_16x16x32_bf16 v[56:59], v[162:165], v[170:173], v[56:59]
	v_mfma_f32_16x16x32_bf16 v[44:47], v[144:147], v[182:185], v[44:47]
	v_mfma_f32_16x16x32_bf16 v[40:43], v[162:165], v[182:185], v[40:43]
	v_mfma_f32_16x16x32_bf16 v[28:31], v[144:147], v[190:193], v[28:31]
	v_mfma_f32_16x16x32_bf16 v[24:27], v[162:165], v[190:193], v[24:27]
	v_mfma_f32_16x16x32_bf16 v[12:15], v[144:147], v[198:201], v[12:15]
	v_mfma_f32_16x16x32_bf16 v[8:11], v[162:165], v[198:201], v[8:11]
	v_mfma_f32_16x16x32_bf16 v[60:63], v[148:151], v[178:181], v[60:63]
	v_mfma_f32_16x16x32_bf16 v[56:59], v[166:169], v[178:181], v[56:59]
	v_mfma_f32_16x16x32_bf16 v[44:47], v[148:151], v[186:189], v[44:47]
	v_mfma_f32_16x16x32_bf16 v[40:43], v[166:169], v[186:189], v[40:43]
	v_mfma_f32_16x16x32_bf16 v[28:31], v[148:151], v[194:197], v[28:31]
	v_mfma_f32_16x16x32_bf16 v[24:27], v[166:169], v[194:197], v[24:27]
	v_mfma_f32_16x16x32_bf16 v[12:15], v[148:151], v[202:205], v[12:15]
	v_mfma_f32_16x16x32_bf16 v[8:11], v[166:169], v[202:205], v[8:11]
	s_setprio 0
	s_barrier
; #define PG8_STAGE(bufoff, gbase, voff) do { _Pragma("unroll") for (int _i = 0; _i < 2; ++_i) \
;         __builtin_amdgcn_global_load_lds((const unsigned*)((const char*)(gbase) + (voff)[_i]), (LAS unsigned*)(lds + (bufoff) + ldsw + _i * 8192), 16, 0, 0); } while (0)
; #define PG8_LDA(dst, b, h) do { _Pragma("unroll") for (int m = 0; m < 4; ++m) _Pragma("unroll") for (int k = 0; k < 2; ++k) dst[m][k] = *(const LAS bf16x8*)(lds + PG8_SA(b, h) + aoff + m * 2048 + k * 1024); } while (0)
; #define PG8_LDB(dst, b, h) do { _Pragma("unroll") for (int n = 0; n < 2; ++n) _Pragma("unroll") for (int k = 0; k < 2; ++k) dst[n][k] = *(const LAS bf16x8*)(lds + PG8_SB(b, h) + boff + n * 2048 + k * 1024); } while (0)
; #define PG8_MMA(ai, bj, At, Bt) do { __builtin_amdgcn_s_setprio(1); _Pragma("unroll") for (int m = 0; m < 4; ++m) _Pragma("unroll") for (int n = 0; n < 2; ++n) _Pragma("unroll") for (int k = 0; k < 2; ++k) \
;         acc[ai][bj][m][n] = __builtin_amdgcn_mfma_f32_16x16x32_bf16(Bt[n][k], At[m][k], acc[ai][bj][m][n], 0, 0, 0); __builtin_amdgcn_s_setprio(0); } while (0)
; #define PG8_WAIT_V(n) asm volatile("s_waitcnt vmcnt(" #n ")" ::: "memory")
; #define PG8_WAIT_L(n) asm volatile("s_waitcnt lgkmcnt(" #n ")" ::: "memory")
; #define PG8_BAR __builtin_amdgcn_s_barrier()
; #define PG8_SCHED __builtin_amdgcn_sched_barrier(0)
; template <class Epi>
; __device__ __forceinline__ void gemm_phase(LAS unsigned char* lds, const Gemm g, const StaticOrder& S, const Epi& E) {
;     ...
;             PG8_STAGE(PG8_SB(0, 1), b2 + hstepB, voffB);
;             PG8_WAIT_V(6); PG8_BAR; PG8_MMA(1, 1, At, B1); PG8_BAR;
;             PG8_LDB(B0, 1, 0); PG8_SCHED; PG8_LDA(At, 1, 0); PG8_STAGE(PG8_SA(0, 1), a2 + hstepA, voffA);
;             PG8_WAIT_L(8); PG8_BAR; PG8_WAIT_L(0); PG8_MMA(0, 0, At, B0); PG8_BAR; PG8_SCHED;
;             PG8_LDB(B1, 1, 1); PG8_STAGE(PG8_SB(1, 0), b3, voffB);
;             PG8_BAR; PG8_WAIT_L(0); PG8_MMA(0, 1, At, B1); PG8_BAR;
;             PG8_LDA(At, 1, 1); PG8_STAGE(PG8_SA(1, 0), a3, voffA);
;             PG8_BAR; PG8_WAIT_L(0); PG8_MMA(1, 0, At, B0); PG8_BAR; PG8_SCHED;
	s_add_u32 s54, s34, 0x40000
	s_addc_u32 s55, s35, 0
	s_add_i32 s53, s46, s29
	v_lshl_add_u64 v[144:145], s[54:55], 0, v[130:131]
	s_mov_b32 m0, s53
	s_nop 0
	global_load_lds_dwordx4 v[144:145], off
	v_lshl_add_u64 v[144:145], s[54:55], 0, v[134:135]
	s_add_i32 m0, s53, 0x2000
	s_nop 0
	global_load_lds_dwordx4 v[144:145], off
	s_waitcnt vmcnt(6)
	s_barrier
	s_setprio 1
	v_mfma_f32_16x16x32_bf16 v[52:55], v[206:209], v[170:173], v[52:55]
	v_mfma_f32_16x16x32_bf16 v[48:51], v[214:217], v[170:173], v[48:51]
	v_mfma_f32_16x16x32_bf16 v[36:39], v[206:209], v[182:185], v[36:39]
	v_mfma_f32_16x16x32_bf16 v[32:35], v[214:217], v[182:185], v[32:35]
	v_mfma_f32_16x16x32_bf16 v[20:23], v[206:209], v[190:193], v[20:23]
	v_mfma_f32_16x16x32_bf16 v[16:19], v[214:217], v[190:193], v[16:19]
	v_mfma_f32_16x16x32_bf16 v[4:7], v[206:209], v[198:201], v[4:7]
	v_mfma_f32_16x16x32_bf16 v[0:3], v[214:217], v[198:201], v[0:3]
	v_mfma_f32_16x16x32_bf16 v[52:55], v[210:213], v[178:181], v[52:55]
	v_mfma_f32_16x16x32_bf16 v[48:51], v[218:221], v[178:181], v[48:51]
	v_mfma_f32_16x16x32_bf16 v[36:39], v[210:213], v[186:189], v[36:39]
	v_mfma_f32_16x16x32_bf16 v[32:35], v[218:221], v[186:189], v[32:35]
	v_mfma_f32_16x16x32_bf16 v[20:23], v[210:213], v[194:197], v[20:23]
	v_mfma_f32_16x16x32_bf16 v[16:19], v[218:221], v[194:197], v[16:19]
	v_mfma_f32_16x16x32_bf16 v[4:7], v[210:213], v[202:205], v[4:7]
	v_mfma_f32_16x16x32_bf16 v[0:3], v[218:221], v[202:205], v[0:3]
	s_setprio 0
	s_add_i32 s53, 0, 0x18000
	v_add_u32_e32 v161, s53, v156
	s_barrier
	ds_read_b128 v[144:147], v161
	ds_read_b128 v[148:151], v161 offset:1024
	ds_read_b128 v[162:165], v161 offset:2048
	ds_read_b128 v[166:169], v161 offset:3072
	s_add_u32 s36, s36, 0x40000
	s_addc_u32 s37, s37, 0
	s_mov_b32 m0, s38
	v_lshl_add_u64 v[206:207], s[36:37], 0, v[128:129]
	ds_read_b128 v[170:173], v159 offset:32768
	ds_read_b128 v[178:181], v159 offset:33792
	ds_read_b128 v[182:185], v159 offset:34816
	ds_read_b128 v[186:189], v159 offset:35840
	ds_read_b128 v[190:193], v159 offset:36864
	ds_read_b128 v[194:197], v159 offset:37888
	ds_read_b128 v[198:201], v159 offset:38912
	ds_read_b128 v[202:205], v159 offset:39936
	global_load_lds_dwordx4 v[206:207], off
	v_lshl_add_u64 v[206:207], s[36:37], 0, v[132:133]
	s_mov_b32 m0, s39
	s_nop 0
	global_load_lds_dwordx4 v[206:207], off
	s_waitcnt lgkmcnt(8)
	s_barrier
	s_waitcnt lgkmcnt(0)
	s_setprio 1
	s_waitcnt lgkmcnt(0)
	v_mfma_f32_16x16x32_bf16 v[124:127], v[144:147], v[170:173], v[124:127]
	v_mfma_f32_16x16x32_bf16 v[120:123], v[162:165], v[170:173], v[120:123]
	v_mfma_f32_16x16x32_bf16 v[108:111], v[144:147], v[182:185], v[108:111]
	v_mfma_f32_16x16x32_bf16 v[104:107], v[162:165], v[182:185], v[104:107]
	v_mfma_f32_16x16x32_bf16 v[92:95], v[144:147], v[190:193], v[92:95]
	v_mfma_f32_16x16x32_bf16 v[88:91], v[162:165], v[190:193], v[88:91]
	v_mfma_f32_16x16x32_bf16 v[76:79], v[144:147], v[198:201], v[76:79]
	v_mfma_f32_16x16x32_bf16 v[72:75], v[162:165], v[198:201], v[72:75]
	v_mfma_f32_16x16x32_bf16 v[124:127], v[148:151], v[178:181], v[124:127]
	v_mfma_f32_16x16x32_bf16 v[120:123], v[166:169], v[178:181], v[120:123]
	v_mfma_f32_16x16x32_bf16 v[108:111], v[148:151], v[186:189], v[108:111]
	v_mfma_f32_16x16x32_bf16 v[104:107], v[166:169], v[186:189], v[104:107]
	v_mfma_f32_16x16x32_bf16 v[92:95], v[148:151], v[194:197], v[92:95]
	v_mfma_f32_16x16x32_bf16 v[88:91], v[166:169], v[194:197], v[88:91]
	v_mfma_f32_16x16x32_bf16 v[76:79], v[148:151], v[202:205], v[76:79]
	v_mfma_f32_16x16x32_bf16 v[72:75], v[166:169], v[202:205], v[72:75]
	s_setprio 0
	s_barrier
	s_add_i32 s36, 0, 0x1c000
	s_add_i32 s37, s53, s29
	v_add_u32_e32 v161, s36, v156
	v_lshl_add_u64 v[174:175], v[174:175], 0, s[10:11]
	s_mov_b32 m0, s37
	ds_read_b128 v[206:209], v161
	ds_read_b128 v[210:213], v161 offset:1024
	ds_read_b128 v[214:217], v161 offset:2048
	ds_read_b128 v[218:221], v161 offset:3072
	global_load_lds_dwordx4 v[174:175], off
	v_lshl_add_u64 v[174:175], v[222:223], 0, s[10:11]
	s_add_i32 m0, s37, 0x2000
	s_nop 0
	global_load_lds_dwordx4 v[174:175], off
	s_barrier
	s_waitcnt lgkmcnt(0)
	s_setprio 1
	s_waitcnt lgkmcnt(0)
	v_mfma_f32_16x16x32_bf16 v[116:119], v[206:209], v[170:173], v[116:119]
	v_mfma_f32_16x16x32_bf16 v[112:115], v[214:217], v[170:173], v[112:115]
	v_mfma_f32_16x16x32_bf16 v[100:103], v[206:209], v[182:185], v[100:103]
	v_mfma_f32_16x16x32_bf16 v[96:99], v[214:217], v[182:185], v[96:99]
	v_mfma_f32_16x16x32_bf16 v[84:87], v[206:209], v[190:193], v[84:87]
	v_mfma_f32_16x16x32_bf16 v[80:83], v[214:217], v[190:193], v[80:83]
	v_mfma_f32_16x16x32_bf16 v[68:71], v[206:209], v[198:201], v[68:71]
	v_mfma_f32_16x16x32_bf16 v[64:67], v[214:217], v[198:201], v[64:67]
	v_mfma_f32_16x16x32_bf16 v[116:119], v[210:213], v[178:181], v[116:119]
	v_mfma_f32_16x16x32_bf16 v[112:115], v[218:221], v[178:181], v[112:115]
	v_mfma_f32_16x16x32_bf16 v[100:103], v[210:213], v[186:189], v[100:103]
	v_mfma_f32_16x16x32_bf16 v[96:99], v[218:221], v[186:189], v[96:99]
	v_mfma_f32_16x16x32_bf16 v[84:87], v[210:213], v[194:197], v[84:87]
	v_mfma_f32_16x16x32_bf16 v[80:83], v[218:221], v[194:197], v[80:83]
	v_mfma_f32_16x16x32_bf16 v[68:71], v[210:213], v[202:205], v[68:71]
	v_mfma_f32_16x16x32_bf16 v[64:67], v[218:221], v[202:205], v[64:67]
	s_setprio 0
	s_mov_b32 m0, s41
	v_lshl_add_u64 v[174:175], v[224:225], 0, s[10:11]
	s_barrier
	ds_read_b128 v[170:173], v159 offset:49152
	ds_read_b128 v[178:181], v159 offset:50176
	ds_read_b128 v[182:185], v159 offset:51200
	ds_read_b128 v[186:189], v159 offset:52224
	ds_read_b128 v[190:193], v159 offset:53248
	ds_read_b128 v[194:197], v159 offset:54272
	ds_read_b128 v[198:201], v159 offset:55296
	ds_read_b128 v[202:205], v159 offset:56320
	global_load_lds_dwordx4 v[174:175], off
	v_lshl_add_u64 v[174:175], v[226:227], 0, s[10:11]
	s_mov_b32 m0, s42
	s_nop 0
	global_load_lds_dwordx4 v[174:175], off
	s_barrier
; __device__ __forceinline__ unsigned pk2(float lo, float hi) { f32x2 v; v.x = lo; v.y = hi; return __builtin_bit_cast(unsigned, __builtin_convertvector(v, hwbf2)); }
; #define PG8_STAGE(bufoff, gbase, voff) do { _Pragma("unroll") for (int _i = 0; _i < 2; ++_i) \
;         __builtin_amdgcn_global_load_lds((const unsigned*)((const char*)(gbase) + (voff)[_i]), (LAS unsigned*)(lds + (bufoff) + ldsw + _i * 8192), 16, 0, 0); } while (0)
; #define PG8_MMA(ai, bj, At, Bt) do { __builtin_amdgcn_s_setprio(1); _Pragma("unroll") for (int m = 0; m < 4; ++m) _Pragma("unroll") for (int n = 0; n < 2; ++n) _Pragma("unroll") for (int k = 0; k < 2; ++k) \
;         acc[ai][bj][m][n] = __builtin_amdgcn_mfma_f32_16x16x32_bf16(Bt[n][k], At[m][k], acc[ai][bj][m][n], 0, 0, 0); __builtin_amdgcn_s_setprio(0); } while (0)
; #define PG8_WAIT_V(n) asm volatile("s_waitcnt vmcnt(" #n ")" ::: "memory")
; #define PG8_BAR __builtin_amdgcn_s_barrier()
; template <class Epi>
; __device__ __forceinline__ void gemm_phase(LAS unsigned char* lds, const Gemm g, const StaticOrder& S, const Epi& E) {
;     ...
;             PG8_STAGE(PG8_SB(1, 1), b3 + hstepB, voffB);
;             PG8_WAIT_V(6); PG8_BAR; PG8_MMA(1, 1, At, B1); PG8_BAR;
;     __device__ __forceinline__ void operator()(const f32x4 (&acc)[2][2][4][2], const pg8::Unit& u, int wr, int wc, int fr, int fq) const {
;         const int row0 = u.pm * 256 + wr * 64 + fr, col0 = u.pn * 256 + wc * 32 + 8 * fq;
; #pragma unroll
;         for (int ai = 0; ai < 2; ++ai)
; #pragma unroll
;             for (int m = 0; m < 4; ++m) { const int row = row0 + ai * 128 + m * 16; const float s = rstd[row]; bf16_t* rowp = O + (size_t)row * ldc + col0;
; #pragma unroll
;                 for (int bj = 0; bj < 2; ++bj) { const f32x4 v0 = acc[ai][bj][m][0] * s, v1 = acc[ai][bj][m][1] * s;
;                     u32x4 w; w.x = pk2(v0[0], v0[1]); w.y = pk2(v0[2], v0[3]); w.z = pk2(v1[0], v1[1]); w.w = pk2(v1[2], v1[3]);
;                     *(u32x4*)(rowp + bj * 128) = w; } }
	s_waitcnt lgkmcnt(0)
	s_setprio 1
	s_waitcnt lgkmcnt(0)
	v_mfma_f32_16x16x32_bf16 v[60:63], v[144:147], v[170:173], v[60:63]
	v_mfma_f32_16x16x32_bf16 v[56:59], v[162:165], v[170:173], v[56:59]
	v_mfma_f32_16x16x32_bf16 v[44:47], v[144:147], v[182:185], v[44:47]
	v_mfma_f32_16x16x32_bf16 v[40:43], v[162:165], v[182:185], v[40:43]
	v_mfma_f32_16x16x32_bf16 v[28:31], v[144:147], v[190:193], v[28:31]
	v_mfma_f32_16x16x32_bf16 v[24:27], v[162:165], v[190:193], v[24:27]
	v_mfma_f32_16x16x32_bf16 v[12:15], v[144:147], v[198:201], v[12:15]
	v_mfma_f32_16x16x32_bf16 v[8:11], v[162:165], v[198:201], v[8:11]
	v_mfma_f32_16x16x32_bf16 v[60:63], v[148:151], v[178:181], v[60:63]
	v_mfma_f32_16x16x32_bf16 v[56:59], v[166:169], v[178:181], v[56:59]
	v_mfma_f32_16x16x32_bf16 v[44:47], v[148:151], v[186:189], v[44:47]
	v_mfma_f32_16x16x32_bf16 v[40:43], v[166:169], v[186:189], v[40:43]
	v_mfma_f32_16x16x32_bf16 v[28:31], v[148:151], v[194:197], v[28:31]
	v_mfma_f32_16x16x32_bf16 v[24:27], v[166:169], v[194:197], v[24:27]
	v_mfma_f32_16x16x32_bf16 v[12:15], v[148:151], v[202:205], v[12:15]
	v_mfma_f32_16x16x32_bf16 v[8:11], v[166:169], v[202:205], v[8:11]
	s_setprio 0
	s_barrier
	s_add_u32 s34, s34, 0x40080
	s_addc_u32 s35, s35, 0
	s_add_i32 s36, s36, s29
	v_lshl_add_u64 v[144:145], s[34:35], 0, v[130:131]
	s_mov_b32 m0, s36
	s_nop 0
	global_load_lds_dwordx4 v[144:145], off
	v_lshl_add_u64 v[144:145], s[34:35], 0, v[134:135]
	s_add_i32 m0, s36, 0x2000
	s_nop 0
	global_load_lds_dwordx4 v[144:145], off
	s_waitcnt vmcnt(6)
	s_barrier
	s_setprio 1
	v_mfma_f32_16x16x32_bf16 v[52:55], v[206:209], v[170:173], v[52:55]
	v_mfma_f32_16x16x32_bf16 v[48:51], v[214:217], v[170:173], v[48:51]
	v_mfma_f32_16x16x32_bf16 v[36:39], v[206:209], v[182:185], v[36:39]
	v_mfma_f32_16x16x32_bf16 v[32:35], v[214:217], v[182:185], v[32:35]
	v_mfma_f32_16x16x32_bf16 v[20:23], v[206:209], v[190:193], v[20:23]
	v_mfma_f32_16x16x32_bf16 v[16:19], v[214:217], v[190:193], v[16:19]
	v_mfma_f32_16x16x32_bf16 v[4:7], v[206:209], v[198:201], v[4:7]
	v_mfma_f32_16x16x32_bf16 v[0:3], v[214:217], v[198:201], v[0:3]
	v_mfma_f32_16x16x32_bf16 v[52:55], v[210:213], v[178:181], v[52:55]
	v_mfma_f32_16x16x32_bf16 v[48:51], v[218:221], v[178:181], v[48:51]
	v_mfma_f32_16x16x32_bf16 v[36:39], v[210:213], v[186:189], v[36:39]
	v_mfma_f32_16x16x32_bf16 v[32:35], v[218:221], v[186:189], v[32:35]
	v_mfma_f32_16x16x32_bf16 v[20:23], v[210:213], v[194:197], v[20:23]
	v_mfma_f32_16x16x32_bf16 v[16:19], v[218:221], v[194:197], v[16:19]
	v_mfma_f32_16x16x32_bf16 v[4:7], v[210:213], v[202:205], v[4:7]
	v_mfma_f32_16x16x32_bf16 v[0:3], v[218:221], v[202:205], v[0:3]
	s_setprio 0
	s_add_i32 s52, s52, 2
	s_add_u32 s30, s30, 0x100
	s_addc_u32 s31, s31, 0
	s_add_u32 s50, s50, 0x100
	s_addc_u32 s51, s51, 0
	s_cmp_gt_u32 s52, 13
	s_barrier
	s_cbranch_scc0 .LBB0_162
	v_lshl_add_u32 v148, s24, 8, v155
	v_ashrrev_i32_e32 v149, 31, v148
	v_lshl_add_u64 v[144:145], v[148:149], 2, s[8:9]
	global_load_dword v178, v[144:145], off
	global_load_dword v180, v[144:145], off offset:64
	global_load_dword v182, v[144:145], off offset:128
	global_load_dword v184, v[144:145], off offset:192
	global_load_dword v186, v[144:145], off offset:512
	global_load_dword v188, v[144:145], off offset:576
	global_load_dword v190, v[144:145], off offset:640
	global_load_dword v192, v[144:145], off offset:704
	v_lshl_or_b32 v146, s47, 8, v157
	v_ashrrev_i32_e32 v147, 31, v146
	v_lshlrev_b64 v[166:167], 12, v[148:149]
	v_or_b32_e32 v164, 16, v148
	v_lshlrev_b64 v[150:151], 1, v[146:147]
	v_lshl_add_u64 v[146:147], s[6:7], 0, v[166:167]
	v_ashrrev_i32_e32 v165, 31, v164
	v_lshl_add_u64 v[146:147], v[146:147], 0, v[150:151]
	v_lshl_add_u64 v[166:167], v[164:165], 2, s[8:9]
	s_mov_b32 s13, 0x80000
	s_mov_b64 s[30:31], 0x80000
	s_mov_b64 s[36:37], 0xb0000
	s_mov_b32 s47, s12
	s_mov_b32 s24, s14
	s_mov_b64 s[34:35], s[20:21]
	s_waitcnt vmcnt(7)
	v_pk_mul_f32 v[126:127], v[126:127], v[178:179] op_sel_hi:[1,0]
	v_pk_mul_f32 v[124:125], v[124:125], v[178:179] op_sel_hi:[1,0]
	v_pk_mul_f32 v[122:123], v[122:123], v[178:179] op_sel_hi:[1,0]
	v_pk_mul_f32 v[120:121], v[120:121], v[178:179] op_sel_hi:[1,0]
	v_pk_mul_f32 v[118:119], v[118:119], v[178:179] op_sel_hi:[1,0]
	v_pk_mul_f32 v[116:117], v[116:117], v[178:179] op_sel_hi:[1,0]
	v_pk_mul_f32 v[168:169], v[114:115], v[178:179] op_sel_hi:[1,0]
	v_pk_mul_f32 v[162:163], v[112:113], v[178:179] op_sel_hi:[1,0]
	v_cvt_pk_bf16_f32 v112, v124, v125
	v_cvt_pk_bf16_f32 v113, v126, v127
	v_cvt_pk_bf16_f32 v114, v120, v121
	v_cvt_pk_bf16_f32 v115, v122, v123
	v_cvt_pk_bf16_f32 v116, v116, v117
	v_cvt_pk_bf16_f32 v117, v118, v119
	v_cvt_pk_bf16_f32 v118, v162, v163
	v_cvt_pk_bf16_f32 v119, v168, v169
	global_store_dwordx4 v[146:147], v[112:115], off
	global_store_dwordx4 v[146:147], v[116:119], off offset:256
	v_or_b32_e32 v114, 32, v148
	v_lshlrev_b64 v[116:117], 12, v[164:165]
	v_lshl_add_u64 v[116:117], s[6:7], 0, v[116:117]
	v_ashrrev_i32_e32 v115, 31, v114
	v_lshl_add_u64 v[116:117], v[116:117], 0, v[150:151]
	v_lshl_add_u64 v[118:119], v[114:115], 2, s[8:9]
	s_waitcnt vmcnt(8)
; __device__ __forceinline__ unsigned pk2(float lo, float hi) { f32x2 v; v.x = lo; v.y = hi; return __builtin_bit_cast(unsigned, __builtin_convertvector(v, hwbf2)); }
;     __device__ __forceinline__ void operator()(const f32x4 (&acc)[2][2][4][2], const pg8::Unit& u, int wr, int wc, int fr, int fq) const {
;     ...
;             for (int m = 0; m < 4; ++m) { const int row = row0 + ai * 128 + m * 16; const float s = rstd[row]; bf16_t* rowp = O + (size_t)row * ldc + col0;
; #pragma unroll
;                 for (int bj = 0; bj < 2; ++bj) { const f32x4 v0 = acc[ai][bj][m][0] * s, v1 = acc[ai][bj][m][1] * s;
;                     u32x4 w; w.x = pk2(v0[0], v0[1]); w.y = pk2(v0[2], v0[3]); w.z = pk2(v1[0], v1[1]); w.w = pk2(v1[2], v1[3]);
;                     *(u32x4*)(rowp + bj * 128) = w; } }
	v_pk_mul_f32 v[110:111], v[110:111], v[180:181] op_sel_hi:[1,0]
	v_pk_mul_f32 v[108:109], v[108:109], v[180:181] op_sel_hi:[1,0]
	v_pk_mul_f32 v[106:107], v[106:107], v[180:181] op_sel_hi:[1,0]
	v_pk_mul_f32 v[104:105], v[104:105], v[180:181] op_sel_hi:[1,0]
	v_pk_mul_f32 v[102:103], v[102:103], v[180:181] op_sel_hi:[1,0]
	v_pk_mul_f32 v[100:101], v[100:101], v[180:181] op_sel_hi:[1,0]
	v_pk_mul_f32 v[120:121], v[98:99], v[180:181] op_sel_hi:[1,0]
	v_pk_mul_f32 v[112:113], v[96:97], v[180:181] op_sel_hi:[1,0]
	v_cvt_pk_bf16_f32 v96, v108, v109
	v_cvt_pk_bf16_f32 v97, v110, v111
	v_cvt_pk_bf16_f32 v98, v104, v105
	v_cvt_pk_bf16_f32 v99, v106, v107
	v_cvt_pk_bf16_f32 v100, v100, v101
	v_cvt_pk_bf16_f32 v101, v102, v103
	v_cvt_pk_bf16_f32 v102, v112, v113
	v_cvt_pk_bf16_f32 v103, v120, v121
	global_store_dwordx4 v[116:117], v[96:99], off
	global_store_dwordx4 v[116:117], v[100:103], off offset:256
	v_or_b32_e32 v98, 48, v148
	v_lshlrev_b64 v[100:101], 12, v[114:115]
	v_lshl_add_u64 v[100:101], s[6:7], 0, v[100:101]
	v_ashrrev_i32_e32 v99, 31, v98
	v_lshl_add_u64 v[100:101], v[100:101], 0, v[150:151]
	v_lshl_add_u64 v[102:103], v[98:99], 2, s[8:9]
	s_waitcnt vmcnt(9)
	v_pk_mul_f32 v[94:95], v[94:95], v[182:183] op_sel_hi:[1,0]
	v_pk_mul_f32 v[92:93], v[92:93], v[182:183] op_sel_hi:[1,0]
	v_pk_mul_f32 v[90:91], v[90:91], v[182:183] op_sel_hi:[1,0]
	v_pk_mul_f32 v[88:89], v[88:89], v[182:183] op_sel_hi:[1,0]
	v_pk_mul_f32 v[86:87], v[86:87], v[182:183] op_sel_hi:[1,0]
	v_pk_mul_f32 v[84:85], v[84:85], v[182:183] op_sel_hi:[1,0]
	v_pk_mul_f32 v[104:105], v[82:83], v[182:183] op_sel_hi:[1,0]
	v_pk_mul_f32 v[96:97], v[80:81], v[182:183] op_sel_hi:[1,0]
	v_cvt_pk_bf16_f32 v80, v92, v93
	v_cvt_pk_bf16_f32 v81, v94, v95
	v_cvt_pk_bf16_f32 v82, v88, v89
	v_cvt_pk_bf16_f32 v83, v90, v91
	v_cvt_pk_bf16_f32 v84, v84, v85
	v_cvt_pk_bf16_f32 v85, v86, v87
	v_cvt_pk_bf16_f32 v86, v96, v97
	v_cvt_pk_bf16_f32 v87, v104, v105
	global_store_dwordx4 v[100:101], v[80:83], off
	global_store_dwordx4 v[100:101], v[84:87], off offset:256
	v_lshlrev_b64 v[82:83], 12, v[98:99]
	v_lshl_add_u64 v[82:83], s[6:7], 0, v[82:83]
	v_lshl_add_u64 v[82:83], v[82:83], 0, v[150:151]
	s_waitcnt vmcnt(10)
	v_pk_mul_f32 v[78:79], v[78:79], v[184:185] op_sel_hi:[1,0]
	v_pk_mul_f32 v[76:77], v[76:77], v[184:185] op_sel_hi:[1,0]
	v_pk_mul_f32 v[74:75], v[74:75], v[184:185] op_sel_hi:[1,0]
	v_pk_mul_f32 v[72:73], v[72:73], v[184:185] op_sel_hi:[1,0]
	v_pk_mul_f32 v[70:71], v[70:71], v[184:185] op_sel_hi:[1,0]
	v_pk_mul_f32 v[68:69], v[68:69], v[184:185] op_sel_hi:[1,0]
	v_pk_mul_f32 v[84:85], v[66:67], v[184:185] op_sel_hi:[1,0]
	v_pk_mul_f32 v[80:81], v[64:65], v[184:185] op_sel_hi:[1,0]
	v_cvt_pk_bf16_f32 v64, v76, v77
	v_cvt_pk_bf16_f32 v65, v78, v79
	v_cvt_pk_bf16_f32 v66, v72, v73
	v_cvt_pk_bf16_f32 v67, v74, v75
	v_cvt_pk_bf16_f32 v68, v68, v69
	v_cvt_pk_bf16_f32 v69, v70, v71
	v_cvt_pk_bf16_f32 v70, v80, v81
	v_cvt_pk_bf16_f32 v71, v84, v85
	global_store_dwordx4 v[82:83], v[64:67], off
	global_store_dwordx4 v[82:83], v[68:71], off offset:256
	v_lshl_add_u64 v[66:67], v[146:147], 0, s[30:31]
	v_add_co_u32_e32 v68, vcc, s13, v146
	s_mov_b32 s13, 0x90000
	s_nop 0
	v_addc_co_u32_e32 v69, vcc, 0, v147, vcc
	s_mov_b64 s[30:31], 0x90000
	s_waitcnt vmcnt(11)
; __device__ __forceinline__ unsigned pk2(float lo, float hi) { f32x2 v; v.x = lo; v.y = hi; return __builtin_bit_cast(unsigned, __builtin_convertvector(v, hwbf2)); }
; #define PG8_WAIT_V(n) asm volatile("s_waitcnt vmcnt(" #n ")" ::: "memory")
; #define PG8_BAR __builtin_amdgcn_s_barrier()
; template <class Epi>
; __device__ __forceinline__ void gemm_phase(LAS unsigned char* lds, const Gemm g, const StaticOrder& S, const Epi& E) {
;     ...
;     PG8_WAIT_V(0);
;     if (wr == 0) PG8_BAR;
;     PG8_BAR;
;     __device__ __forceinline__ void operator()(const f32x4 (&acc)[2][2][4][2], const pg8::Unit& u, int wr, int wc, int fr, int fq) const {
;     ...
;             for (int m = 0; m < 4; ++m) { const int row = row0 + ai * 128 + m * 16; const float s = rstd[row]; bf16_t* rowp = O + (size_t)row * ldc + col0;
; #pragma unroll
;                 for (int bj = 0; bj < 2; ++bj) { const f32x4 v0 = acc[ai][bj][m][0] * s, v1 = acc[ai][bj][m][1] * s;
;                     u32x4 w; w.x = pk2(v0[0], v0[1]); w.y = pk2(v0[2], v0[3]); w.z = pk2(v1[0], v1[1]); w.w = pk2(v1[2], v1[3]);
;                     *(u32x4*)(rowp + bj * 128) = w; } }
	v_pk_mul_f32 v[62:63], v[62:63], v[186:187] op_sel_hi:[1,0]
	v_pk_mul_f32 v[60:61], v[60:61], v[186:187] op_sel_hi:[1,0]
	v_pk_mul_f32 v[58:59], v[58:59], v[186:187] op_sel_hi:[1,0]
	v_pk_mul_f32 v[56:57], v[56:57], v[186:187] op_sel_hi:[1,0]
	v_pk_mul_f32 v[54:55], v[54:55], v[186:187] op_sel_hi:[1,0]
	v_pk_mul_f32 v[52:53], v[52:53], v[186:187] op_sel_hi:[1,0]
	v_pk_mul_f32 v[70:71], v[50:51], v[186:187] op_sel_hi:[1,0]
	v_pk_mul_f32 v[64:65], v[48:49], v[186:187] op_sel_hi:[1,0]
	v_cvt_pk_bf16_f32 v48, v60, v61
	v_cvt_pk_bf16_f32 v49, v62, v63
	v_cvt_pk_bf16_f32 v50, v56, v57
	v_cvt_pk_bf16_f32 v51, v58, v59
	v_cvt_pk_bf16_f32 v52, v52, v53
	v_cvt_pk_bf16_f32 v53, v54, v55
	v_cvt_pk_bf16_f32 v54, v64, v65
	v_cvt_pk_bf16_f32 v55, v70, v71
	global_store_dwordx4 v[68:69], v[48:51], off
	global_store_dwordx4 v[66:67], v[52:55], off offset:256
	v_lshl_add_u64 v[50:51], v[146:147], 0, s[30:31]
	v_add_co_u32_e32 v52, vcc, s13, v146
	s_mov_b32 s13, 0xa0000
	s_nop 0
	v_addc_co_u32_e32 v53, vcc, 0, v147, vcc
	s_mov_b64 s[30:31], 0xa0000
	s_waitcnt vmcnt(12)
	v_pk_mul_f32 v[46:47], v[46:47], v[188:189] op_sel_hi:[1,0]
	v_pk_mul_f32 v[44:45], v[44:45], v[188:189] op_sel_hi:[1,0]
	v_pk_mul_f32 v[42:43], v[42:43], v[188:189] op_sel_hi:[1,0]
	v_pk_mul_f32 v[40:41], v[40:41], v[188:189] op_sel_hi:[1,0]
	v_pk_mul_f32 v[38:39], v[38:39], v[188:189] op_sel_hi:[1,0]
	v_pk_mul_f32 v[36:37], v[36:37], v[188:189] op_sel_hi:[1,0]
	v_pk_mul_f32 v[54:55], v[34:35], v[188:189] op_sel_hi:[1,0]
	v_pk_mul_f32 v[48:49], v[32:33], v[188:189] op_sel_hi:[1,0]
	v_cvt_pk_bf16_f32 v32, v44, v45
	v_cvt_pk_bf16_f32 v33, v46, v47
	v_cvt_pk_bf16_f32 v34, v40, v41
	v_cvt_pk_bf16_f32 v35, v42, v43
	v_cvt_pk_bf16_f32 v36, v36, v37
	v_cvt_pk_bf16_f32 v37, v38, v39
	v_cvt_pk_bf16_f32 v38, v48, v49
	v_cvt_pk_bf16_f32 v39, v54, v55
	global_store_dwordx4 v[52:53], v[32:35], off
	global_store_dwordx4 v[50:51], v[36:39], off offset:256
	v_lshl_add_u64 v[34:35], v[146:147], 0, s[30:31]
	v_add_co_u32_e32 v36, vcc, s13, v146
	s_mov_b32 s13, 0xb0000
	s_nop 0
	v_addc_co_u32_e32 v37, vcc, 0, v147, vcc
	s_and_b64 vcc, exec, s[2:3]
	s_mov_b64 s[30:31], s[16:17]
	s_waitcnt vmcnt(13)
	v_pk_mul_f32 v[30:31], v[30:31], v[190:191] op_sel_hi:[1,0]
	v_pk_mul_f32 v[28:29], v[28:29], v[190:191] op_sel_hi:[1,0]
	v_pk_mul_f32 v[26:27], v[26:27], v[190:191] op_sel_hi:[1,0]
	v_pk_mul_f32 v[24:25], v[24:25], v[190:191] op_sel_hi:[1,0]
	v_pk_mul_f32 v[22:23], v[22:23], v[190:191] op_sel_hi:[1,0]
	v_pk_mul_f32 v[20:21], v[20:21], v[190:191] op_sel_hi:[1,0]
	v_pk_mul_f32 v[38:39], v[18:19], v[190:191] op_sel_hi:[1,0]
	v_pk_mul_f32 v[32:33], v[16:17], v[190:191] op_sel_hi:[1,0]
	v_cvt_pk_bf16_f32 v16, v28, v29
	v_cvt_pk_bf16_f32 v17, v30, v31
	v_cvt_pk_bf16_f32 v18, v24, v25
	v_cvt_pk_bf16_f32 v19, v26, v27
	v_cvt_pk_bf16_f32 v20, v20, v21
	v_cvt_pk_bf16_f32 v21, v22, v23
	v_cvt_pk_bf16_f32 v22, v32, v33
	v_cvt_pk_bf16_f32 v23, v38, v39
	global_store_dwordx4 v[36:37], v[16:19], off
	global_store_dwordx4 v[34:35], v[20:23], off offset:256
	v_lshl_add_u64 v[18:19], v[146:147], 0, s[36:37]
	v_add_co_u32_e64 v20, s[2:3], s13, v146
	s_waitcnt vmcnt(14)
	v_pk_mul_f32 v[14:15], v[14:15], v[192:193] op_sel_hi:[1,0]
	v_pk_mul_f32 v[12:13], v[12:13], v[192:193] op_sel_hi:[1,0]
	v_pk_mul_f32 v[10:11], v[10:11], v[192:193] op_sel_hi:[1,0]
	v_pk_mul_f32 v[8:9], v[8:9], v[192:193] op_sel_hi:[1,0]
	v_addc_co_u32_e64 v21, s[2:3], 0, v147, s[2:3]
	v_pk_mul_f32 v[6:7], v[6:7], v[192:193] op_sel_hi:[1,0]
	v_pk_mul_f32 v[4:5], v[4:5], v[192:193] op_sel_hi:[1,0]
	v_pk_mul_f32 v[22:23], v[2:3], v[192:193] op_sel_hi:[1,0]
	v_pk_mul_f32 v[16:17], v[0:1], v[192:193] op_sel_hi:[1,0]
	v_cvt_pk_bf16_f32 v0, v12, v13
	v_cvt_pk_bf16_f32 v1, v14, v15
	v_cvt_pk_bf16_f32 v2, v8, v9
	v_cvt_pk_bf16_f32 v3, v10, v11
	v_cvt_pk_bf16_f32 v4, v4, v5
	v_cvt_pk_bf16_f32 v5, v6, v7
	v_cvt_pk_bf16_f32 v6, v16, v17
	v_cvt_pk_bf16_f32 v7, v22, v23
	global_store_dwordx4 v[20:21], v[0:3], off
	global_store_dwordx4 v[18:19], v[4:7], off offset:256
	s_cbranch_vccz .LBB0_155
	s_waitcnt vmcnt(0)
	s_cmpk_gt_u32 s23, 0xff
	s_cbranch_scc1 .LBB0_166
	s_barrier

; #define PG8_STAGE(bufoff, gbase, voff) do { _Pragma("unroll") for (int _i = 0; _i < 2; ++_i) \
;         __builtin_amdgcn_global_load_lds((const unsigned*)((const char*)(gbase) + (voff)[_i]), (LAS unsigned*)(lds + (bufoff) + ldsw + _i * 8192), 16, 0, 0); } while (0)
; #define PG8_LDA(dst, b, h) do { _Pragma("unroll") for (int m = 0; m < 4; ++m) _Pragma("unroll") for (int k = 0; k < 2; ++k) dst[m][k] = *(const LAS bf16x8*)(lds + PG8_SA(b, h) + aoff + m * 2048 + k * 1024); } while (0)
; #define PG8_LDB(dst, b, h) do { _Pragma("unroll") for (int n = 0; n < 2; ++n) _Pragma("unroll") for (int k = 0; k < 2; ++k) dst[n][k] = *(const LAS bf16x8*)(lds + PG8_SB(b, h) + boff + n * 2048 + k * 1024); } while (0)
; #define PG8_MMA(ai, bj, At, Bt) do { __builtin_amdgcn_s_setprio(1); _Pragma("unroll") for (int m = 0; m < 4; ++m) _Pragma("unroll") for (int n = 0; n < 2; ++n) _Pragma("unroll") for (int k = 0; k < 2; ++k) \
;         acc[ai][bj][m][n] = __builtin_amdgcn_mfma_f32_16x16x32_bf16(Bt[n][k], At[m][k], acc[ai][bj][m][n], 0, 0, 0); __builtin_amdgcn_s_setprio(0); } while (0)
; #define PG8_WAIT_L(n) asm volatile("s_waitcnt lgkmcnt(" #n ")" ::: "memory")
; #define PG8_BAR __builtin_amdgcn_s_barrier()
; #define PG8_SCHED __builtin_amdgcn_sched_barrier(0)
; template <class Epi>
; __device__ __forceinline__ void gemm_phase(LAS unsigned char* lds, const Gemm g, const StaticOrder& S, const Epi& E) {
;     ...
;             PG8_LDB(B0, 0, 0); PG8_SCHED; PG8_LDA(At, 0, 0); PG8_STAGE(PG8_SA(1, 1), a1 + hstepA, voffA);
;             PG8_WAIT_L(8); PG8_BAR; PG8_WAIT_L(0); PG8_MMA(0, 0, At, B0); PG8_BAR; PG8_SCHED;
;             PG8_LDB(B1, 0, 1); PG8_STAGE(PG8_SB(0, 0), b2, voffB);
;             PG8_BAR; PG8_WAIT_L(0); PG8_MMA(0, 1, At, B1); PG8_BAR;
;             PG8_LDA(At, 0, 1); PG8_STAGE(PG8_SA(0, 0), a2, voffA);
;             PG8_BAR; PG8_WAIT_L(0); PG8_MMA(1, 0, At, B0); PG8_BAR; PG8_SCHED;
;             PG8_STAGE(PG8_SB(0, 1), b2 + hstepB, voffB);
.LBB0_1132:
	ds_read_b128 v[96:99], v218
	ds_read_b128 v[100:103], v218 offset:1024
	ds_read_b128 v[104:107], v218 offset:2048
	ds_read_b128 v[108:111], v218 offset:3072
	s_add_u32 s2, s38, 0x100
	s_addc_u32 s3, s39, 0
	s_cmp_eq_u32 s47, 12
	s_cselect_b32 s43, s35, s3
	s_cselect_b32 s42, s34, s2
	s_cselect_b32 s41, s5, s46
	s_cselect_b32 s40, s31, s45
	v_lshl_add_u64 v[194:195], s[38:39], 0, v[186:187]
	s_add_i32 m0, s48, 0xc000
	ds_read_b128 v[144:147], v219
	ds_read_b128 v[148:151], v219 offset:1024
	ds_read_b128 v[152:155], v219 offset:2048
	ds_read_b128 v[156:159], v219 offset:3072
	ds_read_b128 v[160:163], v219 offset:4096
	ds_read_b128 v[164:167], v219 offset:5120
	ds_read_b128 v[168:171], v219 offset:6144
	ds_read_b128 v[172:175], v219 offset:7168
	global_load_lds_dwordx4 v[194:195], off
	v_lshl_add_u64 v[194:195], s[38:39], 0, v[188:189]
	s_add_i32 m0, s48, 0xe000
	s_nop 0
	global_load_lds_dwordx4 v[194:195], off
	s_waitcnt lgkmcnt(8)
	s_barrier
	s_waitcnt lgkmcnt(0)
	s_setprio 1
	s_waitcnt lgkmcnt(0)
	v_mfma_f32_16x16x32_bf16 v[140:143], v[96:99], v[144:147], v[140:143]
	v_mfma_f32_16x16x32_bf16 v[92:95], v[104:107], v[144:147], v[92:95]
	v_mfma_f32_16x16x32_bf16 v[136:139], v[96:99], v[152:155], v[136:139]
	v_mfma_f32_16x16x32_bf16 v[88:91], v[104:107], v[152:155], v[88:91]
	v_mfma_f32_16x16x32_bf16 v[132:135], v[96:99], v[160:163], v[132:135]
	v_mfma_f32_16x16x32_bf16 v[84:87], v[104:107], v[160:163], v[84:87]
	v_mfma_f32_16x16x32_bf16 v[128:131], v[96:99], v[168:171], v[128:131]
	v_mfma_f32_16x16x32_bf16 v[80:83], v[104:107], v[168:171], v[80:83]
	v_mfma_f32_16x16x32_bf16 v[140:143], v[100:103], v[148:151], v[140:143]
	v_mfma_f32_16x16x32_bf16 v[92:95], v[108:111], v[148:151], v[92:95]
	v_mfma_f32_16x16x32_bf16 v[136:139], v[100:103], v[156:159], v[136:139]
	v_mfma_f32_16x16x32_bf16 v[88:91], v[108:111], v[156:159], v[88:91]
	v_mfma_f32_16x16x32_bf16 v[132:135], v[100:103], v[164:167], v[132:135]
	v_mfma_f32_16x16x32_bf16 v[84:87], v[108:111], v[164:167], v[84:87]
	v_mfma_f32_16x16x32_bf16 v[128:131], v[100:103], v[172:175], v[128:131]
	v_mfma_f32_16x16x32_bf16 v[80:83], v[108:111], v[172:175], v[80:83]
	s_setprio 0
	s_barrier
	s_add_i32 s38, s63, s33
	v_lshl_add_u64 v[210:211], s[40:41], 0, v[180:181]
	s_mov_b32 m0, s38
	ds_read_b128 v[194:197], v220
	ds_read_b128 v[198:201], v220 offset:1024
	ds_read_b128 v[202:205], v220 offset:2048
	ds_read_b128 v[206:209], v220 offset:3072
	global_load_lds_dwordx4 v[210:211], off
	v_lshl_add_u64 v[224:225], s[40:41], 0, v[184:185]
	s_add_i32 m0, s38, 0x2000
	s_nop 0
	global_load_lds_dwordx4 v[224:225], off
	s_barrier
	s_waitcnt lgkmcnt(0)
	s_setprio 1
	s_waitcnt lgkmcnt(0)
	v_mfma_f32_16x16x32_bf16 v[124:127], v[194:197], v[144:147], v[124:127]
	v_mfma_f32_16x16x32_bf16 v[76:79], v[202:205], v[144:147], v[76:79]
	v_mfma_f32_16x16x32_bf16 v[120:123], v[194:197], v[152:155], v[120:123]
	v_mfma_f32_16x16x32_bf16 v[72:75], v[202:205], v[152:155], v[72:75]
	v_mfma_f32_16x16x32_bf16 v[116:119], v[194:197], v[160:163], v[116:119]
	v_mfma_f32_16x16x32_bf16 v[68:71], v[202:205], v[160:163], v[68:71]
	v_mfma_f32_16x16x32_bf16 v[112:115], v[194:197], v[168:171], v[112:115]
	v_mfma_f32_16x16x32_bf16 v[64:67], v[202:205], v[168:171], v[64:67]
	v_mfma_f32_16x16x32_bf16 v[124:127], v[198:201], v[148:151], v[124:127]
	v_mfma_f32_16x16x32_bf16 v[76:79], v[206:209], v[148:151], v[76:79]
	v_mfma_f32_16x16x32_bf16 v[120:123], v[198:201], v[156:159], v[120:123]
	v_mfma_f32_16x16x32_bf16 v[72:75], v[206:209], v[156:159], v[72:75]
	v_mfma_f32_16x16x32_bf16 v[116:119], v[198:201], v[164:167], v[116:119]
	v_mfma_f32_16x16x32_bf16 v[68:71], v[206:209], v[164:167], v[68:71]
	v_mfma_f32_16x16x32_bf16 v[112:115], v[198:201], v[172:175], v[112:115]
	v_mfma_f32_16x16x32_bf16 v[64:67], v[206:209], v[172:175], v[64:67]
	s_setprio 0
	s_mov_b32 m0, s48
	v_lshl_add_u64 v[226:227], s[42:43], 0, v[178:179]
	s_barrier
	ds_read_b128 v[144:147], v219 offset:16384
	ds_read_b128 v[148:151], v219 offset:17408
	ds_read_b128 v[152:155], v219 offset:18432
	ds_read_b128 v[156:159], v219 offset:19456
	ds_read_b128 v[160:163], v219 offset:20480
	ds_read_b128 v[164:167], v219 offset:21504
	ds_read_b128 v[168:171], v219 offset:22528
	ds_read_b128 v[172:175], v219 offset:23552
	global_load_lds_dwordx4 v[226:227], off
	v_lshl_add_u64 v[228:229], s[42:43], 0, v[182:183]
	s_mov_b32 m0, s49
	s_nop 0
	global_load_lds_dwordx4 v[228:229], off
	s_barrier
	s_waitcnt lgkmcnt(0)
	s_setprio 1
	s_waitcnt lgkmcnt(0)
	v_mfma_f32_16x16x32_bf16 v[60:63], v[96:99], v[144:147], v[60:63]
	v_mfma_f32_16x16x32_bf16 v[28:31], v[104:107], v[144:147], v[28:31]
	v_mfma_f32_16x16x32_bf16 v[56:59], v[96:99], v[152:155], v[56:59]
	v_mfma_f32_16x16x32_bf16 v[24:27], v[104:107], v[152:155], v[24:27]
	v_mfma_f32_16x16x32_bf16 v[52:55], v[96:99], v[160:163], v[52:55]
	v_mfma_f32_16x16x32_bf16 v[20:23], v[104:107], v[160:163], v[20:23]
	v_mfma_f32_16x16x32_bf16 v[48:51], v[96:99], v[168:171], v[48:51]
	v_mfma_f32_16x16x32_bf16 v[16:19], v[104:107], v[168:171], v[16:19]
	v_mfma_f32_16x16x32_bf16 v[60:63], v[100:103], v[148:151], v[60:63]
	v_mfma_f32_16x16x32_bf16 v[28:31], v[108:111], v[148:151], v[28:31]
	v_mfma_f32_16x16x32_bf16 v[56:59], v[100:103], v[156:159], v[56:59]
	v_mfma_f32_16x16x32_bf16 v[24:27], v[108:111], v[156:159], v[24:27]
	v_mfma_f32_16x16x32_bf16 v[52:55], v[100:103], v[164:167], v[52:55]
	v_mfma_f32_16x16x32_bf16 v[20:23], v[108:111], v[164:167], v[20:23]
	v_mfma_f32_16x16x32_bf16 v[48:51], v[100:103], v[172:175], v[48:51]
	v_mfma_f32_16x16x32_bf16 v[16:19], v[108:111], v[172:175], v[16:19]
	s_setprio 0
	s_barrier
; #define PG8_STAGE(bufoff, gbase, voff) do { _Pragma("unroll") for (int _i = 0; _i < 2; ++_i) \
;         __builtin_amdgcn_global_load_lds((const unsigned*)((const char*)(gbase) + (voff)[_i]), (LAS unsigned*)(lds + (bufoff) + ldsw + _i * 8192), 16, 0, 0); } while (0)
; #define PG8_LDA(dst, b, h) do { _Pragma("unroll") for (int m = 0; m < 4; ++m) _Pragma("unroll") for (int k = 0; k < 2; ++k) dst[m][k] = *(const LAS bf16x8*)(lds + PG8_SA(b, h) + aoff + m * 2048 + k * 1024); } while (0)
; #define PG8_LDB(dst, b, h) do { _Pragma("unroll") for (int n = 0; n < 2; ++n) _Pragma("unroll") for (int k = 0; k < 2; ++k) dst[n][k] = *(const LAS bf16x8*)(lds + PG8_SB(b, h) + boff + n * 2048 + k * 1024); } while (0)
; #define PG8_MMA(ai, bj, At, Bt) do { __builtin_amdgcn_s_setprio(1); _Pragma("unroll") for (int m = 0; m < 4; ++m) _Pragma("unroll") for (int n = 0; n < 2; ++n) _Pragma("unroll") for (int k = 0; k < 2; ++k) \
;         acc[ai][bj][m][n] = __builtin_amdgcn_mfma_f32_16x16x32_bf16(Bt[n][k], At[m][k], acc[ai][bj][m][n], 0, 0, 0); __builtin_amdgcn_s_setprio(0); } while (0)
; #define PG8_WAIT_V(n) asm volatile("s_waitcnt vmcnt(" #n ")" ::: "memory")
; #define PG8_WAIT_L(n) asm volatile("s_waitcnt lgkmcnt(" #n ")" ::: "memory")
; #define PG8_BAR __builtin_amdgcn_s_barrier()
; #define PG8_SCHED __builtin_amdgcn_sched_barrier(0)
; template <class Epi>
; __device__ __forceinline__ void gemm_phase(LAS unsigned char* lds, const Gemm g, const StaticOrder& S, const Epi& E) {
;     ...
;             PG8_STAGE(PG8_SB(0, 1), b2 + hstepB, voffB);
;             PG8_WAIT_V(6); PG8_BAR; PG8_MMA(1, 1, At, B1); PG8_BAR;
;             PG8_LDB(B0, 1, 0); PG8_SCHED; PG8_LDA(At, 1, 0); PG8_STAGE(PG8_SA(0, 1), a2 + hstepA, voffA);
;             PG8_WAIT_L(8); PG8_BAR; PG8_WAIT_L(0); PG8_MMA(0, 0, At, B0); PG8_BAR; PG8_SCHED;
;             PG8_LDB(B1, 1, 1); PG8_STAGE(PG8_SB(1, 0), b3, voffB);
;             PG8_BAR; PG8_WAIT_L(0); PG8_MMA(0, 1, At, B1); PG8_BAR;
;             PG8_LDA(At, 1, 1); PG8_STAGE(PG8_SA(1, 0), a3, voffA);
;             PG8_BAR; PG8_WAIT_L(0); PG8_MMA(1, 0, At, B0); PG8_BAR; PG8_SCHED;
	s_add_u32 s38, s40, 0x40000
	s_addc_u32 s39, s41, 0
	s_add_i32 s71, s22, s33
	v_lshl_add_u64 v[96:97], s[38:39], 0, v[180:181]
	s_mov_b32 m0, s71
	s_nop 0
	global_load_lds_dwordx4 v[96:97], off
	v_lshl_add_u64 v[96:97], s[38:39], 0, v[184:185]
	s_add_i32 m0, s71, 0x2000
	s_nop 0
	global_load_lds_dwordx4 v[96:97], off
	s_waitcnt vmcnt(6)
	s_barrier
	s_setprio 1
	v_mfma_f32_16x16x32_bf16 v[44:47], v[194:197], v[144:147], v[44:47]
	v_mfma_f32_16x16x32_bf16 v[12:15], v[202:205], v[144:147], v[12:15]
	v_mfma_f32_16x16x32_bf16 v[40:43], v[194:197], v[152:155], v[40:43]
	v_mfma_f32_16x16x32_bf16 v[8:11], v[202:205], v[152:155], v[8:11]
	v_mfma_f32_16x16x32_bf16 v[36:39], v[194:197], v[160:163], v[36:39]
	v_mfma_f32_16x16x32_bf16 v[4:7], v[202:205], v[160:163], v[4:7]
	v_mfma_f32_16x16x32_bf16 v[32:35], v[194:197], v[168:171], v[32:35]
	v_mfma_f32_16x16x32_bf16 v[0:3], v[202:205], v[168:171], v[0:3]
	v_mfma_f32_16x16x32_bf16 v[44:47], v[198:201], v[148:151], v[44:47]
	v_mfma_f32_16x16x32_bf16 v[12:15], v[206:209], v[148:151], v[12:15]
	v_mfma_f32_16x16x32_bf16 v[40:43], v[198:201], v[156:159], v[40:43]
	v_mfma_f32_16x16x32_bf16 v[8:11], v[206:209], v[156:159], v[8:11]
	v_mfma_f32_16x16x32_bf16 v[36:39], v[198:201], v[164:167], v[36:39]
	v_mfma_f32_16x16x32_bf16 v[4:7], v[206:209], v[164:167], v[4:7]
	v_mfma_f32_16x16x32_bf16 v[32:35], v[198:201], v[172:175], v[32:35]
	v_mfma_f32_16x16x32_bf16 v[0:3], v[206:209], v[172:175], v[0:3]
	s_setprio 0
	s_add_i32 s71, 0, 0x18000
	v_add_u32_e32 v108, s71, v217
	s_barrier
	ds_read_b128 v[96:99], v108
	ds_read_b128 v[100:103], v108 offset:1024
	ds_read_b128 v[104:107], v108 offset:2048
	ds_read_b128 v[108:111], v108 offset:3072
	s_add_u32 s38, s42, 0x3e000
	s_addc_u32 s39, s43, 0
	s_mov_b32 m0, s50
	v_lshl_add_u64 v[194:195], s[38:39], 0, v[178:179]
	ds_read_b128 v[144:147], v219 offset:32768
	ds_read_b128 v[148:151], v219 offset:33792
	ds_read_b128 v[152:155], v219 offset:34816
	ds_read_b128 v[156:159], v219 offset:35840
	ds_read_b128 v[160:163], v219 offset:36864
	ds_read_b128 v[164:167], v219 offset:37888
	ds_read_b128 v[168:171], v219 offset:38912
	ds_read_b128 v[172:175], v219 offset:39936
	global_load_lds_dwordx4 v[194:195], off
	v_lshl_add_u64 v[194:195], s[38:39], 0, v[182:183]
	s_mov_b32 m0, s51
	s_nop 0
	global_load_lds_dwordx4 v[194:195], off
	s_waitcnt lgkmcnt(8)
	s_barrier
	s_waitcnt lgkmcnt(0)
	s_setprio 1
	s_waitcnt lgkmcnt(0)
	v_mfma_f32_16x16x32_bf16 v[140:143], v[96:99], v[144:147], v[140:143]
	v_mfma_f32_16x16x32_bf16 v[92:95], v[104:107], v[144:147], v[92:95]
	v_mfma_f32_16x16x32_bf16 v[136:139], v[96:99], v[152:155], v[136:139]
	v_mfma_f32_16x16x32_bf16 v[88:91], v[104:107], v[152:155], v[88:91]
	v_mfma_f32_16x16x32_bf16 v[132:135], v[96:99], v[160:163], v[132:135]
	v_mfma_f32_16x16x32_bf16 v[84:87], v[104:107], v[160:163], v[84:87]
	v_mfma_f32_16x16x32_bf16 v[128:131], v[96:99], v[168:171], v[128:131]
	v_mfma_f32_16x16x32_bf16 v[80:83], v[104:107], v[168:171], v[80:83]
	v_mfma_f32_16x16x32_bf16 v[140:143], v[100:103], v[148:151], v[140:143]
	v_mfma_f32_16x16x32_bf16 v[92:95], v[108:111], v[148:151], v[92:95]
	v_mfma_f32_16x16x32_bf16 v[136:139], v[100:103], v[156:159], v[136:139]
	v_mfma_f32_16x16x32_bf16 v[88:91], v[108:111], v[156:159], v[88:91]
	v_mfma_f32_16x16x32_bf16 v[132:135], v[100:103], v[164:167], v[132:135]
	v_mfma_f32_16x16x32_bf16 v[84:87], v[108:111], v[164:167], v[84:87]
	v_mfma_f32_16x16x32_bf16 v[128:131], v[100:103], v[172:175], v[128:131]
	v_mfma_f32_16x16x32_bf16 v[80:83], v[108:111], v[172:175], v[80:83]
	s_setprio 0
	s_barrier
	s_add_i32 s42, 0, 0x1c000
	s_add_i32 s38, s71, s33
	v_add_u32_e32 v206, s42, v217
	v_lshl_add_u64 v[210:211], v[210:211], 0, s[12:13]
	s_mov_b32 m0, s38
	ds_read_b128 v[194:197], v206
	ds_read_b128 v[198:201], v206 offset:1024
	ds_read_b128 v[202:205], v206 offset:2048
	ds_read_b128 v[206:209], v206 offset:3072
	global_load_lds_dwordx4 v[210:211], off
	v_lshl_add_u64 v[210:211], v[224:225], 0, s[12:13]
	s_add_i32 m0, s38, 0x2000
	s_nop 0
	global_load_lds_dwordx4 v[210:211], off
	s_barrier
	s_waitcnt lgkmcnt(0)
	s_setprio 1
	s_waitcnt lgkmcnt(0)
	v_mfma_f32_16x16x32_bf16 v[124:127], v[194:197], v[144:147], v[124:127]
	v_mfma_f32_16x16x32_bf16 v[76:79], v[202:205], v[144:147], v[76:79]
	v_mfma_f32_16x16x32_bf16 v[120:123], v[194:197], v[152:155], v[120:123]
	v_mfma_f32_16x16x32_bf16 v[72:75], v[202:205], v[152:155], v[72:75]
	v_mfma_f32_16x16x32_bf16 v[116:119], v[194:197], v[160:163], v[116:119]
	v_mfma_f32_16x16x32_bf16 v[68:71], v[202:205], v[160:163], v[68:71]
	v_mfma_f32_16x16x32_bf16 v[112:115], v[194:197], v[168:171], v[112:115]
	v_mfma_f32_16x16x32_bf16 v[64:67], v[202:205], v[168:171], v[64:67]
	v_mfma_f32_16x16x32_bf16 v[124:127], v[198:201], v[148:151], v[124:127]
	v_mfma_f32_16x16x32_bf16 v[76:79], v[206:209], v[148:151], v[76:79]
	v_mfma_f32_16x16x32_bf16 v[120:123], v[198:201], v[156:159], v[120:123]
	v_mfma_f32_16x16x32_bf16 v[72:75], v[206:209], v[156:159], v[72:75]
	v_mfma_f32_16x16x32_bf16 v[116:119], v[198:201], v[164:167], v[116:119]
	v_mfma_f32_16x16x32_bf16 v[68:71], v[206:209], v[164:167], v[68:71]
	v_mfma_f32_16x16x32_bf16 v[112:115], v[198:201], v[172:175], v[112:115]
	v_mfma_f32_16x16x32_bf16 v[64:67], v[206:209], v[172:175], v[64:67]
	s_setprio 0
	s_mov_b32 m0, s55
	v_lshl_add_u64 v[210:211], v[226:227], 0, s[12:13]
	s_barrier
	ds_read_b128 v[144:147], v219 offset:49152
	ds_read_b128 v[148:151], v219 offset:50176
	ds_read_b128 v[152:155], v219 offset:51200
	ds_read_b128 v[156:159], v219 offset:52224
	ds_read_b128 v[160:163], v219 offset:53248
	ds_read_b128 v[164:167], v219 offset:54272
	ds_read_b128 v[168:171], v219 offset:55296
	ds_read_b128 v[172:175], v219 offset:56320
	global_load_lds_dwordx4 v[210:211], off
	v_lshl_add_u64 v[210:211], v[228:229], 0, s[12:13]
	s_mov_b32 m0, s56
	s_nop 0
	global_load_lds_dwordx4 v[210:211], off
	s_barrier
; #define LAS __attribute__((address_space(3)))
; #define PG8_STAGE(bufoff, gbase, voff) do { _Pragma("unroll") for (int _i = 0; _i < 2; ++_i) \
;         __builtin_amdgcn_global_load_lds((const unsigned*)((const char*)(gbase) + (voff)[_i]), (LAS unsigned*)(lds + (bufoff) + ldsw + _i * 8192), 16, 0, 0); } while (0)
; #define PG8_LDA(dst, b, h) do { _Pragma("unroll") for (int m = 0; m < 4; ++m) _Pragma("unroll") for (int k = 0; k < 2; ++k) dst[m][k] = *(const LAS bf16x8*)(lds + PG8_SA(b, h) + aoff + m * 2048 + k * 1024); } while (0)
; #define PG8_LDB(dst, b, h) do { _Pragma("unroll") for (int n = 0; n < 2; ++n) _Pragma("unroll") for (int k = 0; k < 2; ++k) dst[n][k] = *(const LAS bf16x8*)(lds + PG8_SB(b, h) + boff + n * 2048 + k * 1024); } while (0)
; template <class Epi>
; __device__ __forceinline__ void gemm_phase(LAS unsigned char* lds, const Gemm g, const StaticOrder& S, const Epi& E) {
;     ...
;             PG8_WAIT_L(8); PG8_BAR; PG8_WAIT_L(0); PG8_MMA(0, 0, At, B0); PG8_BAR; PG8_SCHED;
;             PG8_LDB(B1, 1, 1); PG8_STAGE(PG8_SB(1, 0), b3, voffB);
;             PG8_BAR; PG8_WAIT_L(0); PG8_MMA(0, 1, At, B1); PG8_BAR;
;             PG8_LDA(At, 1, 1); PG8_STAGE(PG8_SA(1, 0), a3, voffA);
;             PG8_BAR; PG8_WAIT_L(0); PG8_MMA(1, 0, At, B0); PG8_BAR; PG8_SCHED;
;             PG8_STAGE(PG8_SB(1, 1), b3 + hstepB, voffB);
;             PG8_WAIT_V(6); PG8_BAR; PG8_MMA(1, 1, At, B1); PG8_BAR;
;     __device__ __forceinline__ void operator()(const f32x4 (&acc)[2][2][4][2], const pg8::Unit& u, int wr, int wc, int fr_, int fq_) const {
;         int fr = fr_, fq = fq_; asm volatile("" : "+v"(fr), "+v"(fq));
;         LAS unsigned char* slab = xl + (wr * 4 + wc) * SLAB_BYTES;
;         const int lane = fq * 16 + fr, cq = lane & 3, rs = lane >> 2;
;         const int j0 = u.pn * 128 + wc * 32 + 8 * cq;
;         float sc[2][4];
; #pragma unroll
;         for (int ai = 0; ai < 2; ++ai)
; #pragma unroll
;             for (int m = 0; m < 4; ++m) { const int row = 248 * u.pm + 62 * (2 * ai + wr) - 2 + 16 * m + fr; const int rc = row < 0 ? 0 : (row < R ? row : R - 1); const float sv = rstd3[rc]; sc[ai][m] = (row >= 0 && row < R) ? sv : 0.f; }
;         f32x4 wn[4];
;         { const int colb = j0; wn[0] = *(const f32x4*)(cw + colb); wn[1] = *(const f32x4*)(cw + NUP + colb); wn[2] = *(const f32x4*)(cw + 2 * NUP + colb); wn[3] = *(const f32x4*)(cb + colb); }
	s_waitcnt lgkmcnt(0)
	s_setprio 1
	s_waitcnt lgkmcnt(0)
	v_mfma_f32_16x16x32_bf16 v[60:63], v[96:99], v[144:147], v[60:63]
	v_mfma_f32_16x16x32_bf16 v[28:31], v[104:107], v[144:147], v[28:31]
	v_mfma_f32_16x16x32_bf16 v[56:59], v[96:99], v[152:155], v[56:59]
	v_mfma_f32_16x16x32_bf16 v[24:27], v[104:107], v[152:155], v[24:27]
	v_mfma_f32_16x16x32_bf16 v[52:55], v[96:99], v[160:163], v[52:55]
	v_mfma_f32_16x16x32_bf16 v[20:23], v[104:107], v[160:163], v[20:23]
	v_mfma_f32_16x16x32_bf16 v[48:51], v[96:99], v[168:171], v[48:51]
	v_mfma_f32_16x16x32_bf16 v[16:19], v[104:107], v[168:171], v[16:19]
	v_mfma_f32_16x16x32_bf16 v[60:63], v[100:103], v[148:151], v[60:63]
	v_mfma_f32_16x16x32_bf16 v[28:31], v[108:111], v[148:151], v[28:31]
	v_mfma_f32_16x16x32_bf16 v[56:59], v[100:103], v[156:159], v[56:59]
	v_mfma_f32_16x16x32_bf16 v[24:27], v[108:111], v[156:159], v[24:27]
	v_mfma_f32_16x16x32_bf16 v[52:55], v[100:103], v[164:167], v[52:55]
	v_mfma_f32_16x16x32_bf16 v[20:23], v[108:111], v[164:167], v[20:23]
	v_mfma_f32_16x16x32_bf16 v[48:51], v[100:103], v[172:175], v[48:51]
	v_mfma_f32_16x16x32_bf16 v[16:19], v[108:111], v[172:175], v[16:19]
	s_setprio 0
	s_barrier
	s_add_u32 s38, s40, 0x40080
	s_addc_u32 s39, s41, 0
	s_add_i32 s40, s42, s33
	v_lshl_add_u64 v[96:97], s[38:39], 0, v[180:181]
	s_mov_b32 m0, s40
	s_nop 0
	global_load_lds_dwordx4 v[96:97], off
	v_lshl_add_u64 v[96:97], s[38:39], 0, v[184:185]
	s_add_i32 m0, s40, 0x2000
	s_nop 0
	global_load_lds_dwordx4 v[96:97], off
	s_waitcnt vmcnt(6)
	s_barrier
	s_setprio 1
	v_mfma_f32_16x16x32_bf16 v[44:47], v[194:197], v[144:147], v[44:47]
	v_mfma_f32_16x16x32_bf16 v[12:15], v[202:205], v[144:147], v[12:15]
	v_mfma_f32_16x16x32_bf16 v[40:43], v[194:197], v[152:155], v[40:43]
	v_mfma_f32_16x16x32_bf16 v[8:11], v[202:205], v[152:155], v[8:11]
	v_mfma_f32_16x16x32_bf16 v[36:39], v[194:197], v[160:163], v[36:39]
	v_mfma_f32_16x16x32_bf16 v[4:7], v[202:205], v[160:163], v[4:7]
	v_mfma_f32_16x16x32_bf16 v[32:35], v[194:197], v[168:171], v[32:35]
	v_mfma_f32_16x16x32_bf16 v[0:3], v[202:205], v[168:171], v[0:3]
	v_mfma_f32_16x16x32_bf16 v[44:47], v[198:201], v[148:151], v[44:47]
	v_mfma_f32_16x16x32_bf16 v[12:15], v[206:209], v[148:151], v[12:15]
	v_mfma_f32_16x16x32_bf16 v[40:43], v[198:201], v[156:159], v[40:43]
	v_mfma_f32_16x16x32_bf16 v[8:11], v[206:209], v[156:159], v[8:11]
	v_mfma_f32_16x16x32_bf16 v[36:39], v[198:201], v[164:167], v[36:39]
	v_mfma_f32_16x16x32_bf16 v[4:7], v[206:209], v[164:167], v[4:7]
	v_mfma_f32_16x16x32_bf16 v[32:35], v[198:201], v[172:175], v[32:35]
	v_mfma_f32_16x16x32_bf16 v[0:3], v[206:209], v[172:175], v[0:3]
	s_setprio 0
	s_add_i32 s47, s47, 2
	s_add_u32 s45, s45, 0x100
	s_addc_u32 s46, s46, 0
	s_cmp_gt_u32 s47, 13
	s_mov_b64 s[38:39], s[2:3]
	s_barrier
	s_cbranch_scc0 .LBB0_1132
	s_mul_i32 s31, s44, 0xf8
	v_mov_b32_e32 v207, v215
	v_mov_b32_e32 v96, v216
	s_add_i32 s31, s31, -2
	s_lshl_b32 s2, s4, 7
	v_add_u32_e32 v97, s31, v207
	v_add_u32_e32 v168, s57, v97
	v_med3_i32 v98, v168, 0, v222
	v_add_u32_e32 v169, 16, v168
	v_add_u32_e32 v170, 32, v168
	v_lshlrev_b32_e32 v98, 2, v98
	v_med3_i32 v99, v169, 0, v222
	v_med3_i32 v100, v170, 0, v222
	v_add_u32_e32 v209, 48, v168
	v_lshlrev_b32_e32 v99, 2, v99
	v_lshlrev_b32_e32 v100, 2, v100
	global_load_dword v171, v98, s[10:11]
	global_load_dword v204, v99, s[10:11]
	global_load_dword v206, v100, s[10:11]
	v_med3_i32 v98, v209, 0, v222
	v_lshlrev_b32_e32 v98, 2, v98
	global_load_dword v211, v98, s[10:11]
	v_lshl_add_u32 v205, v96, 4, v207
	v_lshlrev_b32_e32 v98, 3, v207
	s_or_b32 s2, s2, s54
	v_and_b32_e32 v225, 24, v98
	v_add_u32_e32 v237, s58, v97
	v_and_b32_e32 v230, -4, v205
	v_lshl_add_u32 v224, v96, 3, s62
	v_med3_i32 v96, v237, 0, v222
	v_add_u32_e32 v233, 16, v237
	v_add_u32_e32 v232, 32, v237
	v_or_b32_e32 v194, s2, v225
	v_mul_lo_u32 v229, v230, 40
	v_lshlrev_b32_e32 v98, 2, v96
	v_med3_i32 v96, v233, 0, v222
	v_med3_i32 v97, v232, 0, v222
	v_ashrrev_i32_e32 v195, 31, v194
	v_subrev_u32_e32 v100, 40, v229
	v_cmp_lt_i32_e64 s[2:3], 3, v205
	v_readlane_b32 s64, v254, 23
	v_lshlrev_b32_e32 v102, 2, v96
	v_lshlrev_b32_e32 v103, 2, v97
	v_lshlrev_b64 v[96:97], 2, v[194:195]
	v_cndmask_b32_e64 v100, 0, v100, s[2:3]
	v_readlane_b32 s74, v254, 33
	v_readlane_b32 s75, v254, 34
	v_add_u32_e32 v144, s62, v100
	v_add_u32_e32 v226, v144, v225
	v_lshl_add_u64 v[196:197], s[74:75], 0, v[96:97]
	v_add_co_u32_e32 v144, vcc, s52, v196
	v_lshl_add_u64 v[198:199], s[14:15], 0, v[96:97]
	s_nop 0
	v_addc_co_u32_e32 v145, vcc, 0, v197, vcc
	v_add_co_u32_e32 v146, vcc, s52, v198
	v_add_u32_e32 v231, 48, v237
	s_nop 0
	v_addc_co_u32_e32 v147, vcc, 0, v199, vcc
	v_med3_i32 v99, v231, 0, v222
	v_cmp_gt_u32_e32 vcc, s81, v168
	v_add_u32_e32 v101, 0xffffffb0, v229
	v_lshlrev_b32_e32 v99, 2, v99
	v_readlane_b32 s76, v254, 35
	v_readlane_b32 s77, v254, 36
	v_cndmask_b32_e64 v228, 0, v101, s[2:3]
	global_load_dword v238, v98, s[10:11]
	global_load_dword v236, v102, s[10:11]
	global_load_dword v235, v103, s[10:11]
	global_load_dword v234, v99, s[10:11]
	v_lshl_add_u64 v[200:201], s[16:17], 0, v[96:97]
	v_lshl_add_u64 v[202:203], s[76:77], 0, v[96:97]
	global_load_dwordx4 v[104:107], v[196:197], off offset:16
	global_load_dwordx4 v[164:167], v[196:197], off
	global_load_dwordx4 v[100:103], v[198:199], off offset:16
	global_load_dwordx4 v[160:163], v[198:199], off
	global_load_dwordx4 v[96:99], v[200:201], off offset:16
	global_load_dwordx4 v[156:159], v[200:201], off
	global_load_dwordx4 v[108:111], v[202:203], off offset:16
	global_load_dwordx4 v[172:175], v[202:203], off
	global_load_dwordx4 v[148:151], v[144:145], off offset:3072
	global_load_dwordx4 v[152:155], v[146:147], off offset:3072
	s_add_i32 s46, s31, s57
	v_add_u32_e32 v241, s46, v230
	v_readlane_b32 s65, v254, 24
	v_readlane_b32 s66, v254, 25
	v_readlane_b32 s67, v254, 26
	v_readlane_b32 s68, v254, 27
	v_readlane_b32 s69, v254, 28
	v_readlane_b32 s70, v254, 29
	v_readlane_b32 s71, v254, 30
	v_readlane_b32 s72, v254, 31
	v_readlane_b32 s73, v254, 32
	v_readlane_b32 s78, v254, 37
	v_readlane_b32 s79, v254, 38
	s_waitcnt vmcnt(0)
; #define LAS __attribute__((address_space(3)))
; __device__ __forceinline__ float bf2f(unsigned v) { return __uint_as_float(v << 16); }
;     __device__ __forceinline__ void operator()(const f32x4 (&acc)[2][2][4][2], const pg8::Unit& u, int wr, int wc, int fr_, int fq_) const {
;     ...
;             if (sp < 7) { const int sq = sp + 1, n2 = (sq >> 1) & 1, bj2 = sq & 1, colb = bj2 * DFF + j0 + 4 * n2;
;                 wn[0] = *(const f32x4*)(cw + colb); wn[1] = *(const f32x4*)(cw + NUP + colb); wn[2] = *(const f32x4*)(cw + 2 * NUP + colb); wn[3] = *(const f32x4*)(cb + colb); }
; #pragma unroll
;             for (int m = 0; m < 4; ++m) { const f32x4 v = acc[ai][bj][m][n] * sc[ai][m];
;                 u32x2 w; w.x = pk2(v[0], v[1]); w.y = pk2(v[2], v[3]); *(LAS u32x2*)(slab + (16 * m + fr) * SLAB_LD + fq * 8) = w; }
;             f32x4 p2, p1;
;             { const int h1 = rs > 0 ? 4 * rs - 1 : 0, h2 = rs > 0 ? 4 * rs - 2 : 0;
;                 const u32x2 q1 = *(const LAS u32x2*)(slab + h1 * SLAB_LD + cq * 8), q2 = *(const LAS u32x2*)(slab + h2 * SLAB_LD + cq * 8);
;                 p1[0] = bf2f(q1.x & 0xffff); p1[1] = bf2f(q1.x >> 16); p1[2] = bf2f(q1.y & 0xffff); p1[3] = bf2f(q1.y >> 16);
;                 p2[0] = bf2f(q2.x & 0xffff); p2[1] = bf2f(q2.x >> 16); p2[2] = bf2f(q2.y & 0xffff); p2[3] = bf2f(q2.y >> 16); }
; #pragma unroll
;             for (int i = 0; i < 4; ++i) {
;                 const int lr = 4 * rs + i, row = rowbase + lr;
;                 const u32x2 q0 = *(const LAS u32x2*)(slab + lr * SLAB_LD + cq * 8);
;                 f32x4 cur; cur[0] = bf2f(q0.x & 0xffff); cur[1] = bf2f(q0.x >> 16); cur[2] = bf2f(q0.y & 0xffff); cur[3] = bf2f(q0.y >> 16);
;                 const bool smp = row >= RP;
;                 const int t = smp ? ((row - RP) & (DSEQ - 1)) : (row & (SEQ - 1));
;                 const bool valid = (lr >= 2) && (row < R) && (t >= 2);
;                 const f32x4 cv = bb + w0 * p2 + w1 * p1 + w2 * cur;
;                 p2 = p1; p1 = cur;
;                 if (bj == 0) { cgv[i][0] = cv[0]; cgv[i][1] = cv[1]; cgv[i][2] = cv[2]; cgv[i][3] = cv[3]; }
;                 else { u32x2 w; w.x = pk2(gelu_tanh(cgv[i][0]) * cv[0], gelu_tanh(cgv[i][1]) * cv[1]); w.y = pk2(gelu_tanh(cgv[i][2]) * cv[2], gelu_tanh(cgv[i][3]) * cv[3]); if (valid) *(u32x2*)(act + (size_t)row * DFF + j0 + 4 * n) = w; }
	v_cndmask_b32_e32 v210, 0, v171, vcc
	v_cmp_gt_u32_e32 vcc, s81, v169
	v_pk_mul_f32 v[142:143], v[142:143], v[210:211] op_sel_hi:[1,0]
	s_nop 0
	v_cndmask_b32_e32 v208, 0, v204, vcc
	v_cmp_gt_u32_e32 vcc, s81, v170
	v_pk_mul_f32 v[140:141], v[140:141], v[210:211] op_sel_hi:[1,0]
	v_pk_mul_f32 v[138:139], v[138:139], v[208:209] op_sel_hi:[1,0]
	v_cndmask_b32_e32 v206, 0, v206, vcc
	v_cmp_gt_u32_e32 vcc, s81, v209
	v_cvt_pk_bf16_f32 v140, v140, v141
	v_cvt_pk_bf16_f32 v141, v142, v143
	v_cndmask_b32_e32 v204, 0, v211, vcc
	v_add_co_u32_e32 v144, vcc, s52, v200
	v_mul_lo_u32 v142, v207, 40
	s_nop 0
	v_addc_co_u32_e32 v145, vcc, 0, v201, vcc
	v_add_co_u32_e32 v168, vcc, s52, v202
	global_load_dwordx4 v[144:147], v[144:145], off offset:3072
	s_nop 0
	v_addc_co_u32_e32 v169, vcc, 0, v203, vcc
	global_load_dwordx4 v[168:171], v[168:169], off offset:3072
	v_pk_mul_f32 v[136:137], v[136:137], v[208:209] op_sel_hi:[1,0]
	v_pk_mul_f32 v[134:135], v[134:135], v[206:207] op_sel_hi:[1,0]
	v_pk_mul_f32 v[132:133], v[132:133], v[206:207] op_sel_hi:[1,0]
	v_pk_mul_f32 v[130:131], v[130:131], v[204:205] op_sel_hi:[1,0]
	v_pk_mul_f32 v[128:129], v[128:129], v[204:205] op_sel_hi:[1,0]
	v_add_u32_e32 v227, v224, v142
	v_cvt_pk_bf16_f32 v136, v136, v137
	v_cvt_pk_bf16_f32 v137, v138, v139
	v_cvt_pk_bf16_f32 v132, v132, v133
	v_cvt_pk_bf16_f32 v133, v134, v135
	v_cvt_pk_bf16_f32 v128, v128, v129
	v_cvt_pk_bf16_f32 v129, v130, v131
	ds_write_b64 v227, v[140:141]
	ds_write_b64 v227, v[136:137] offset:640
	ds_write_b64 v227, v[132:133] offset:1280
	ds_write_b64 v227, v[128:129] offset:1920
	ds_read_b64 v[128:129], v226
	v_add_u32_e32 v130, s62, v228
	v_add_u32_e32 v132, s62, v225
	v_add_u32_e32 v228, v130, v225
	v_add_u32_e32 v225, v132, v229
	v_or_b32_e32 v229, 3, v205
	v_mul_lo_u32 v133, v229, 40
	v_pk_mul_f32 v[126:127], v[126:127], v[210:211] op_sel_hi:[1,0]
	v_pk_mul_f32 v[124:125], v[124:125], v[210:211] op_sel_hi:[1,0]
	v_pk_mul_f32 v[122:123], v[122:123], v[208:209] op_sel_hi:[1,0]
	v_pk_mul_f32 v[120:121], v[120:121], v[208:209] op_sel_hi:[1,0]
	v_pk_mul_f32 v[118:119], v[118:119], v[206:207] op_sel_hi:[1,0]
	v_pk_mul_f32 v[116:117], v[116:117], v[206:207] op_sel_hi:[1,0]
	v_pk_mul_f32 v[114:115], v[114:115], v[204:205] op_sel_hi:[1,0]
	v_pk_mul_f32 v[112:113], v[112:113], v[204:205] op_sel_hi:[1,0]
	v_add_u32_e32 v224, v132, v133
	v_cvt_pk_bf16_f32 v124, v124, v125
	v_cvt_pk_bf16_f32 v125, v126, v127
	v_cvt_pk_bf16_f32 v120, v120, v121
	v_cvt_pk_bf16_f32 v121, v122, v123
	v_cvt_pk_bf16_f32 v116, v116, v117
	v_cvt_pk_bf16_f32 v117, v118, v119
	v_cvt_pk_bf16_f32 v112, v112, v113
	v_cvt_pk_bf16_f32 v113, v114, v115
	ds_read_b64 v[142:143], v228
	s_waitcnt lgkmcnt(0)
	v_lshlrev_b32_e32 v136, 16, v128
	v_and_b32_e32 v137, 0xffff0000, v128
	v_lshlrev_b32_e32 v138, 16, v129
	v_and_b32_e32 v139, 0xffff0000, v129
	ds_read_b64 v[140:141], v225
	ds_read2_b64 v[128:131], v225 offset0:5 offset1:10
	ds_read_b64 v[132:133], v224
	ds_write_b64 v227, v[124:125]
	ds_write_b64 v227, v[120:121] offset:640
	ds_write_b64 v227, v[116:117] offset:1280
	ds_write_b64 v227, v[112:113] offset:1920
	ds_read_b64 v[112:113], v226
	ds_read_b64 v[114:115], v225
	v_cmp_gt_i32_e32 vcc, s81, v241
	s_and_b64 s[4:5], s[2:3], vcc
	v_cmp_lt_i32_e32 vcc, s82, v241
	s_waitcnt lgkmcnt(8)
	v_lshlrev_b32_e32 v134, 16, v140
	v_and_b32_e32 v135, 0xffff0000, v140
	v_cndmask_b32_e64 v118, v223, 30, vcc
	v_and_b32_e32 v118, v118, v241
	v_cmp_ne_u32_e32 vcc, 0, v118
	v_lshlrev_b32_e32 v116, 16, v141
	v_and_b32_e32 v117, 0xffff0000, v141
	s_waitcnt lgkmcnt(1)
	v_lshlrev_b32_e32 v126, 16, v112
	v_and_b32_e32 v127, 0xffff0000, v112
	v_lshlrev_b32_e32 v140, 16, v113
	v_and_b32_e32 v141, 0xffff0000, v113
	s_waitcnt lgkmcnt(0)
	v_lshlrev_b32_e32 v112, 16, v114
	v_and_b32_e32 v113, 0xffff0000, v114
	v_lshlrev_b32_e32 v114, 16, v115
	v_and_b32_e32 v115, 0xffff0000, v115
	s_and_b64 s[38:39], s[4:5], vcc
	s_waitcnt vmcnt(0)
	s_and_saveexec_b64 s[4:5], s[38:39]
	s_cbranch_execz .LBB0_1135
	v_lshlrev_b32_e32 v122, 16, v142
	v_and_b32_e32 v123, 0xffff0000, v142
	v_lshlrev_b32_e32 v124, 16, v143
	v_and_b32_e32 v125, 0xffff0000, v143
	v_pk_fma_f32 v[122:123], v[164:165], v[122:123], v[172:173]
	v_pk_fma_f32 v[124:125], v[166:167], v[124:125], v[174:175]
	v_pk_fma_f32 v[122:123], v[160:161], v[136:137], v[122:123]
	v_pk_fma_f32 v[124:125], v[162:163], v[138:139], v[124:125]
	v_pk_fma_f32 v[122:123], v[156:157], v[134:135], v[122:123]
	v_pk_fma_f32 v[124:125], v[158:159], v[116:117], v[124:125]
	v_mul_f32_e32 v207, v122, v122
	v_mul_f32_e32 v142, v124, v124
	v_mul_f32_e32 v143, v125, v125
	v_fmamk_f32 v207, v207, 0xbdd2d3e2, v221
	v_mul_f32_e32 v209, v123, v123
	v_fmamk_f32 v142, v142, 0xbdd2d3e2, v221
	v_fmamk_f32 v143, v143, 0xbdd2d3e2, v221
	v_mul_f32_e32 v207, v122, v207
	v_fmamk_f32 v209, v209, 0xbdd2d3e2, v221
	v_mul_f32_e32 v142, v124, v142
	v_mul_f32_e32 v143, v125, v143
	v_exp_f32_e32 v207, v207
	v_mul_f32_e32 v209, v123, v209
	v_exp_f32_e32 v142, v142
	v_exp_f32_e32 v143, v143
	v_exp_f32_e32 v209, v209
	ds_read_b64 v[118:119], v228
	v_add_f32_e32 v207, 1.0, v207
	v_add_f32_e32 v142, 1.0, v142
	v_add_f32_e32 v143, 1.0, v143
	v_rcp_f32_e32 v242, v207
	v_add_f32_e32 v207, 1.0, v209
	v_rcp_f32_e32 v142, v142
	v_rcp_f32_e32 v143, v143
	v_rcp_f32_e32 v243, v207
	s_waitcnt lgkmcnt(0)
	v_lshlrev_b32_e32 v120, 16, v118
	v_and_b32_e32 v121, 0xffff0000, v118
	v_lshlrev_b32_e32 v118, 16, v119
	v_and_b32_e32 v119, 0xffff0000, v119
	v_pk_fma_f32 v[120:121], v[148:149], v[120:121], v[168:169]
	v_pk_fma_f32 v[118:119], v[150:151], v[118:119], v[170:171]
	v_pk_fma_f32 v[120:121], v[152:153], v[126:127], v[120:121]
	v_pk_fma_f32 v[118:119], v[154:155], v[140:141], v[118:119]
	v_pk_fma_f32 v[120:121], v[144:145], v[112:113], v[120:121]
	v_pk_fma_f32 v[118:119], v[146:147], v[114:115], v[118:119]
	v_pk_mul_f32 v[124:125], v[124:125], v[142:143]
	v_pk_mul_f32 v[122:123], v[122:123], v[242:243]
	v_pk_mul_f32 v[118:119], v[124:125], v[118:119]
	v_pk_mul_f32 v[120:121], v[122:123], v[120:121]
	v_cvt_pk_bf16_f32 v119, v118, v119
	v_cvt_pk_bf16_f32 v118, v120, v121
	v_mov_b64_e32 v[120:121], s[8:9]
	v_mad_i64_i32 v[120:121], s[40:41], v241, s83, v[120:121]
	v_lshl_add_u64 v[120:121], v[194:195], 1, v[120:121]
	global_store_dwordx2 v[120:121], v[118:119], off
; #define LAS __attribute__((address_space(3)))
; __device__ __forceinline__ float bf2f(unsigned v) { return __uint_as_float(v << 16); }
; __device__ __forceinline__ unsigned pk2(float lo, float hi) { f32x2 v; v.x = lo; v.y = hi; return __builtin_bit_cast(unsigned, __builtin_convertvector(v, hwbf2)); }
;     __device__ __forceinline__ void operator()(const f32x4 (&acc)[2][2][4][2], const pg8::Unit& u, int wr, int wc, int fr_, int fq_) const {
;     ...
;             for (int i = 0; i < 4; ++i) {
;                 const int lr = 4 * rs + i, row = rowbase + lr;
;                 const u32x2 q0 = *(const LAS u32x2*)(slab + lr * SLAB_LD + cq * 8);
;                 f32x4 cur; cur[0] = bf2f(q0.x & 0xffff); cur[1] = bf2f(q0.x >> 16); cur[2] = bf2f(q0.y & 0xffff); cur[3] = bf2f(q0.y >> 16);
;                 const bool smp = row >= RP;
;                 const int t = smp ? ((row - RP) & (DSEQ - 1)) : (row & (SEQ - 1));
;                 const bool valid = (lr >= 2) && (row < R) && (t >= 2);
;                 const f32x4 cv = bb + w0 * p2 + w1 * p1 + w2 * cur;
;                 p2 = p1; p1 = cur;
;                 if (bj == 0) { cgv[i][0] = cv[0]; cgv[i][1] = cv[1]; cgv[i][2] = cv[2]; cgv[i][3] = cv[3]; }
;                 else { u32x2 w; w.x = pk2(gelu_tanh(cgv[i][0]) * cv[0], gelu_tanh(cgv[i][1]) * cv[1]); w.y = pk2(gelu_tanh(cgv[i][2]) * cv[2], gelu_tanh(cgv[i][3]) * cv[3]); if (valid) *(u32x2*)(act + (size_t)row * DFF + j0 + 4 * n) = w; }
.LBB0_1135:
	s_or_b64 exec, exec, s[4:5]
	v_or_b32_e32 v239, 1, v230
	v_add_u32_e32 v242, s46, v239
	ds_read_b64 v[120:121], v225 offset:40
	v_cmp_gt_i32_e32 vcc, s81, v242
	s_and_b64 s[4:5], s[2:3], vcc
	v_cmp_lt_i32_e32 vcc, s82, v242
	v_lshlrev_b32_e32 v122, 16, v128
	v_and_b32_e32 v123, 0xffff0000, v128
	v_cndmask_b32_e64 v128, v223, 30, vcc
	v_and_b32_e32 v128, v128, v242
	v_cmp_ne_u32_e32 vcc, 0, v128
	v_lshlrev_b32_e32 v124, 16, v129
	v_and_b32_e32 v125, 0xffff0000, v129
	s_waitcnt lgkmcnt(0)
	v_lshlrev_b32_e32 v118, 16, v120
	v_and_b32_e32 v119, 0xffff0000, v120
	v_lshlrev_b32_e32 v120, 16, v121
	v_and_b32_e32 v121, 0xffff0000, v121
	s_and_b64 s[40:41], s[4:5], vcc
	s_and_saveexec_b64 s[4:5], s[40:41]
	s_cbranch_execz .LBB0_1137
	v_pk_fma_f32 v[128:129], v[166:167], v[138:139], v[174:175]
	v_pk_fma_f32 v[136:137], v[164:165], v[136:137], v[172:173]
	v_pk_fma_f32 v[128:129], v[162:163], v[116:117], v[128:129]
	v_pk_fma_f32 v[136:137], v[160:161], v[134:135], v[136:137]
	v_pk_fma_f32 v[128:129], v[158:159], v[124:125], v[128:129]
	v_pk_fma_f32 v[136:137], v[156:157], v[122:123], v[136:137]
	v_pk_fma_f32 v[138:139], v[150:151], v[140:141], v[170:171]
	v_mul_f32_e32 v140, v128, v128
	v_mul_f32_e32 v141, v129, v129
	v_mul_f32_e32 v142, v136, v136
	v_mul_f32_e32 v143, v137, v137
	v_fmamk_f32 v140, v140, 0xbdd2d3e2, v221
	v_fmamk_f32 v141, v141, 0xbdd2d3e2, v221
	v_fmamk_f32 v142, v142, 0xbdd2d3e2, v221
	v_fmamk_f32 v143, v143, 0xbdd2d3e2, v221
	v_mul_f32_e32 v140, v128, v140
	v_mul_f32_e32 v141, v129, v141
	v_mul_f32_e32 v142, v136, v142
	v_mul_f32_e32 v143, v137, v143
	v_exp_f32_e32 v140, v140
	v_exp_f32_e32 v141, v141
	v_exp_f32_e32 v142, v142
	v_exp_f32_e32 v143, v143
	v_add_f32_e32 v140, 1.0, v140
	v_add_f32_e32 v141, 1.0, v141
	v_add_f32_e32 v142, 1.0, v142
	v_add_f32_e32 v143, 1.0, v143
	v_rcp_f32_e32 v140, v140
	v_rcp_f32_e32 v141, v141
	v_rcp_f32_e32 v142, v142
	v_rcp_f32_e32 v143, v143
	v_pk_fma_f32 v[126:127], v[148:149], v[126:127], v[168:169]
	v_pk_fma_f32 v[138:139], v[154:155], v[114:115], v[138:139]
	v_pk_fma_f32 v[126:127], v[152:153], v[112:113], v[126:127]
	v_pk_fma_f32 v[138:139], v[146:147], v[120:121], v[138:139]
	v_pk_fma_f32 v[126:127], v[144:145], v[118:119], v[126:127]
	v_pk_mul_f32 v[128:129], v[128:129], v[140:141]
	v_pk_mul_f32 v[136:137], v[136:137], v[142:143]
	v_pk_mul_f32 v[128:129], v[128:129], v[138:139]
	v_pk_mul_f32 v[126:127], v[136:137], v[126:127]
	v_cvt_pk_bf16_f32 v129, v128, v129
	v_cvt_pk_bf16_f32 v128, v126, v127
	v_mov_b64_e32 v[126:127], s[8:9]
	v_mad_i64_i32 v[126:127], s[42:43], v242, s83, v[126:127]
	v_lshl_add_u64 v[126:127], v[194:195], 1, v[126:127]
	global_store_dwordx2 v[126:127], v[128:129], off
; #define LAS __attribute__((address_space(3)))
; __device__ __forceinline__ float bf2f(unsigned v) { return __uint_as_float(v << 16); }
; __device__ __forceinline__ unsigned pk2(float lo, float hi) { f32x2 v; v.x = lo; v.y = hi; return __builtin_bit_cast(unsigned, __builtin_convertvector(v, hwbf2)); }
;     __device__ __forceinline__ void operator()(const f32x4 (&acc)[2][2][4][2], const pg8::Unit& u, int wr, int wc, int fr_, int fq_) const {
;     ...
;             for (int i = 0; i < 4; ++i) {
;                 const int lr = 4 * rs + i, row = rowbase + lr;
;                 const u32x2 q0 = *(const LAS u32x2*)(slab + lr * SLAB_LD + cq * 8);
;                 f32x4 cur; cur[0] = bf2f(q0.x & 0xffff); cur[1] = bf2f(q0.x >> 16); cur[2] = bf2f(q0.y & 0xffff); cur[3] = bf2f(q0.y >> 16);
;                 const bool smp = row >= RP;
;                 const int t = smp ? ((row - RP) & (DSEQ - 1)) : (row & (SEQ - 1));
;                 const bool valid = (lr >= 2) && (row < R) && (t >= 2);
;                 const f32x4 cv = bb + w0 * p2 + w1 * p1 + w2 * cur;
;                 p2 = p1; p1 = cur;
;                 if (bj == 0) { cgv[i][0] = cv[0]; cgv[i][1] = cv[1]; cgv[i][2] = cv[2]; cgv[i][3] = cv[3]; }
;                 else { u32x2 w; w.x = pk2(gelu_tanh(cgv[i][0]) * cv[0], gelu_tanh(cgv[i][1]) * cv[1]); w.y = pk2(gelu_tanh(cgv[i][2]) * cv[2], gelu_tanh(cgv[i][3]) * cv[3]); if (valid) *(u32x2*)(act + (size_t)row * DFF + j0 + 4 * n) = w; }
.LBB0_1137:
	s_or_b64 exec, exec, s[4:5]
	v_or_b32_e32 v240, 2, v230
	v_add_u32_e32 v243, s46, v240
	ds_read_b64 v[128:129], v225 offset:80
	v_cmp_lt_i32_e64 s[4:5], -1, v205
	v_cmp_gt_i32_e32 vcc, s81, v243
	s_and_b64 s[42:43], s[4:5], vcc
	v_cmp_lt_i32_e32 vcc, s82, v243
	v_lshlrev_b32_e32 v136, 16, v130
	v_and_b32_e32 v137, 0xffff0000, v130
	v_cndmask_b32_e64 v138, v223, 30, vcc
	v_and_b32_e32 v138, v138, v243
	v_cmp_ne_u32_e32 vcc, 0, v138
	v_lshlrev_b32_e32 v130, 16, v131
	v_and_b32_e32 v131, 0xffff0000, v131
	s_waitcnt lgkmcnt(0)
	v_lshlrev_b32_e32 v126, 16, v128
	v_and_b32_e32 v127, 0xffff0000, v128
	v_lshlrev_b32_e32 v128, 16, v129
	v_and_b32_e32 v129, 0xffff0000, v129
	s_and_b64 s[42:43], s[42:43], vcc
	s_and_saveexec_b64 s[44:45], s[42:43]
	s_cbranch_execz .LBB0_1139
	v_pk_fma_f32 v[116:117], v[166:167], v[116:117], v[174:175]
	v_pk_fma_f32 v[134:135], v[164:165], v[134:135], v[172:173]
	v_pk_fma_f32 v[116:117], v[162:163], v[124:125], v[116:117]
	v_pk_fma_f32 v[134:135], v[160:161], v[122:123], v[134:135]
	v_pk_fma_f32 v[116:117], v[158:159], v[130:131], v[116:117]
	v_pk_fma_f32 v[134:135], v[156:157], v[136:137], v[134:135]
	v_mul_f32_e32 v138, v116, v116
	v_mul_f32_e32 v139, v117, v117
	v_fmamk_f32 v138, v138, 0xbdd2d3e2, v221
	v_fmamk_f32 v139, v139, 0xbdd2d3e2, v221
	v_mul_f32_e32 v140, v134, v134
	v_mul_f32_e32 v141, v135, v135
	v_mul_f32_e32 v138, v116, v138
	v_mul_f32_e32 v139, v117, v139
	v_fmamk_f32 v140, v140, 0xbdd2d3e2, v221
	v_fmamk_f32 v141, v141, 0xbdd2d3e2, v221
	v_exp_f32_e32 v138, v138
	v_exp_f32_e32 v139, v139
	v_mul_f32_e32 v140, v134, v140
	v_mul_f32_e32 v141, v135, v141
	v_exp_f32_e32 v140, v140
	v_exp_f32_e32 v141, v141
	v_add_f32_e32 v138, 1.0, v138
	v_add_f32_e32 v139, 1.0, v139
	v_rcp_f32_e32 v138, v138
	v_rcp_f32_e32 v139, v139
	v_add_f32_e32 v140, 1.0, v140
	v_add_f32_e32 v141, 1.0, v141
	v_rcp_f32_e32 v140, v140
	v_rcp_f32_e32 v141, v141
	v_pk_fma_f32 v[114:115], v[150:151], v[114:115], v[170:171]
	v_pk_fma_f32 v[112:113], v[148:149], v[112:113], v[168:169]
	v_pk_fma_f32 v[114:115], v[154:155], v[120:121], v[114:115]
	v_pk_fma_f32 v[112:113], v[152:153], v[118:119], v[112:113]
	v_pk_fma_f32 v[114:115], v[146:147], v[128:129], v[114:115]
	v_pk_mul_f32 v[116:117], v[116:117], v[138:139]
	v_pk_fma_f32 v[112:113], v[144:145], v[126:127], v[112:113]
	v_pk_mul_f32 v[114:115], v[116:117], v[114:115]
	v_pk_mul_f32 v[116:117], v[134:135], v[140:141]
	v_cvt_pk_bf16_f32 v115, v114, v115
	v_pk_mul_f32 v[112:113], v[116:117], v[112:113]
	s_nop 0
	v_cvt_pk_bf16_f32 v114, v112, v113
	v_mov_b64_e32 v[112:113], s[8:9]
	v_mad_i64_i32 v[112:113], s[72:73], v243, s83, v[112:113]
	v_lshl_add_u64 v[112:113], v[194:195], 1, v[112:113]
	global_store_dwordx2 v[112:113], v[114:115], off
.LBB0_1139:
	s_or_b64 exec, exec, s[44:45]
	v_add_u32_e32 v244, s46, v229
	v_cmp_gt_i32_e32 vcc, s81, v244
	s_and_b64 s[44:45], s[4:5], vcc
	v_cmp_lt_i32_e32 vcc, s82, v244
	s_nop 1
	v_cndmask_b32_e64 v112, v223, 30, vcc
	v_and_b32_e32 v112, v112, v244
	v_cmp_ne_u32_e32 vcc, 0, v112
	s_and_b64 s[44:45], s[44:45], vcc
	s_and_saveexec_b64 s[46:47], s[44:45]
	s_cbranch_execz .LBB0_1141
	v_pk_fma_f32 v[114:115], v[164:165], v[122:123], v[172:173]
	v_lshlrev_b32_e32 v116, 16, v132
	v_pk_fma_f32 v[114:115], v[160:161], v[136:137], v[114:115]
	v_and_b32_e32 v117, 0xffff0000, v132
	v_pk_fma_f32 v[114:115], v[156:157], v[116:117], v[114:115]
	ds_read_b64 v[116:117], v224
	v_pk_fma_f32 v[112:113], v[166:167], v[124:125], v[174:175]
	v_lshlrev_b32_e32 v122, 16, v133
	v_pk_fma_f32 v[112:113], v[162:163], v[130:131], v[112:113]
	v_and_b32_e32 v123, 0xffff0000, v133
	v_pk_fma_f32 v[118:119], v[148:149], v[118:119], v[168:169]
	v_pk_fma_f32 v[112:113], v[158:159], v[122:123], v[112:113]
	v_pk_fma_f32 v[118:119], v[152:153], v[126:127], v[118:119]
	s_waitcnt lgkmcnt(0)
	v_lshlrev_b32_e32 v122, 16, v116
	v_and_b32_e32 v123, 0xffff0000, v116
	v_pk_fma_f32 v[118:119], v[144:145], v[122:123], v[118:119]
	v_mul_f32_e32 v122, v112, v112
	v_mul_f32_e32 v123, v113, v113
	v_fmamk_f32 v122, v122, 0xbdd2d3e2, v221
	v_fmamk_f32 v123, v123, 0xbdd2d3e2, v221
	v_mul_f32_e32 v122, v112, v122
	v_mul_f32_e32 v123, v113, v123
	v_exp_f32_e32 v122, v122
	v_exp_f32_e32 v123, v123
	v_pk_fma_f32 v[120:121], v[150:151], v[120:121], v[170:171]
	v_lshlrev_b32_e32 v116, 16, v117
	v_pk_fma_f32 v[120:121], v[154:155], v[128:129], v[120:121]
	v_and_b32_e32 v117, 0xffff0000, v117
	v_pk_fma_f32 v[116:117], v[146:147], v[116:117], v[120:121]
	v_add_f32_e32 v120, 1.0, v122
	v_add_f32_e32 v121, 1.0, v123
	v_mul_f32_e32 v122, v114, v114
	v_mul_f32_e32 v123, v115, v115
	v_fmamk_f32 v122, v122, 0xbdd2d3e2, v221
	v_fmamk_f32 v123, v123, 0xbdd2d3e2, v221
	v_mul_f32_e32 v122, v114, v122
	v_mul_f32_e32 v123, v115, v123
	v_exp_f32_e32 v122, v122
	v_exp_f32_e32 v123, v123
	v_rcp_f32_e32 v120, v120
	v_rcp_f32_e32 v121, v121
	v_add_f32_e32 v122, 1.0, v122
	v_add_f32_e32 v123, 1.0, v123
	v_rcp_f32_e32 v122, v122
	v_rcp_f32_e32 v123, v123
	v_pk_mul_f32 v[112:113], v[112:113], v[120:121]
	v_pk_mul_f32 v[114:115], v[114:115], v[122:123]
	v_pk_mul_f32 v[112:113], v[112:113], v[116:117]
	v_pk_mul_f32 v[114:115], v[114:115], v[118:119]
	v_cvt_pk_bf16_f32 v113, v112, v113
	v_cvt_pk_bf16_f32 v112, v114, v115
	v_mov_b64_e32 v[114:115], s[8:9]
	v_mad_i64_i32 v[114:115], s[72:73], v244, s83, v[114:115]
	v_lshl_add_u64 v[114:115], v[194:195], 1, v[114:115]
	global_store_dwordx2 v[114:115], v[112:113], off
